# conv item mapping blocked: a workgroup covers 16 grid rows x 32 channel groups so the dy-neighbour gate rows are reused inside the workgroup
# speedup vs baseline: 1.0223x; 1.0030x over previous
.Lconv_item:
	v_lshrrev_b32_e32 v233, 9, v230
	v_mul_u32_u24_e32 v232, 0x1746, v233
	v_lshrrev_b32_e32 v232, 16, v232
	v_mul_u32_u24_e32 v234, 11, v232
	v_sub_u32_e32 v233, v233, v234
	v_and_b32_e32 v234, 31, v230
	v_lshl_add_u32 v231, v233, 5, v234
	v_lshlrev_b32_e32 v231, 4, v231
	v_mov_b32_e32 v233, v231
	global_load_dwordx4 v[146:149], v233, s[16:17]
	v_add_u32_e32 v233, 0x1600, v233
	global_load_dwordx4 v[150:153], v233, s[16:17]
	v_add_u32_e32 v233, 0x1600, v233
	global_load_dwordx4 v[154:157], v233, s[16:17]
	v_add_u32_e32 v233, 0x1600, v233
	global_load_dwordx4 v[158:161], v233, s[16:17]
	v_add_u32_e32 v233, 0x1600, v233
	global_load_dwordx4 v[162:165], v233, s[16:17]
	v_add_u32_e32 v233, 0x1600, v233
	global_load_dwordx4 v[166:169], v233, s[16:17]
	v_add_u32_e32 v233, 0x1600, v233
	global_load_dwordx4 v[170:173], v233, s[16:17]
	v_add_u32_e32 v233, 0x1600, v233
	global_load_dwordx4 v[174:177], v233, s[16:17]
	v_add_u32_e32 v233, 0x1600, v233
	global_load_dwordx4 v[178:181], v233, s[16:17]
	v_lshlrev_b32_e32 v234, 1, v231
	global_load_dwordx4 v[72:75], v234, s[18:19]
	global_load_dwordx4 v[76:79], v234, s[18:19] offset:16
	v_bfe_u32 v233, v232, 2, 1
	v_cmp_eq_u32_e64 s[4:5], 0, v233
	v_cmp_eq_u32_e64 s[6:7], 1, v233
	v_bfe_u32 v234, v230, 5, 4
	v_and_b32_e32 v139, 3, v232
	v_lshl_add_u32 v234, v139, 4, v234
	v_cmp_eq_u32_e64 s[0:1], 0, v234
	v_cmp_eq_u32_e64 s[2:3], 63, v234
	v_lshrrev_b32_e32 v139, 3, v232
	v_lshl_add_u32 v234, v139, 6, v234
	v_lshlrev_b32_e32 v234, 6, v234
	v_lshl_add_u32 v234, v233, 5, v234
	v_mul_u32_u24_e32 v234, 0x2c00, v234
	v_add_u32_e32 v139, v234, v231
	v_mov_b32_e32 v140, v139
	v_add_u32_e32 v137, 0x1600, v139
	v_subrev_u32_e32 v233, 0x2c00, v137
	v_cndmask_b32_e64 v137, v233, v137, s[4:5]
	v_mov_b32_e32 v233, 0xb0000
	v_sub_u32_e32 v136, v137, v233
	v_cndmask_b32_e64 v136, v136, v137, s[0:1]
	v_add_u32_e32 v138, v137, v233
	v_cndmask_b32_e64 v138, v138, v137, s[2:3]
	s_waitcnt vmcnt(10)
	v_lshlrev_b32_e32 v0, 16, v146
	v_and_b32_e32 v1, 0xffff0000, v146
	v_lshlrev_b32_e32 v2, 16, v147
	v_and_b32_e32 v3, 0xffff0000, v147
	v_lshlrev_b32_e32 v4, 16, v148
	v_and_b32_e32 v5, 0xffff0000, v148
	v_lshlrev_b32_e32 v6, 16, v149
	v_and_b32_e32 v7, 0xffff0000, v149
	s_waitcnt vmcnt(9)
	v_lshlrev_b32_e32 v8, 16, v150
	v_and_b32_e32 v9, 0xffff0000, v150
	v_lshlrev_b32_e32 v10, 16, v151
	v_and_b32_e32 v11, 0xffff0000, v151
	v_lshlrev_b32_e32 v12, 16, v152
	v_and_b32_e32 v13, 0xffff0000, v152
	v_lshlrev_b32_e32 v14, 16, v153
	v_and_b32_e32 v15, 0xffff0000, v153
	s_waitcnt vmcnt(8)
	v_lshlrev_b32_e32 v16, 16, v154
	v_and_b32_e32 v17, 0xffff0000, v154
	v_lshlrev_b32_e32 v18, 16, v155
	v_and_b32_e32 v19, 0xffff0000, v155
	v_lshlrev_b32_e32 v20, 16, v156
	v_and_b32_e32 v21, 0xffff0000, v156
	v_lshlrev_b32_e32 v22, 16, v157
	v_and_b32_e32 v23, 0xffff0000, v157
	s_waitcnt vmcnt(7)
	v_lshlrev_b32_e32 v24, 16, v158
	v_and_b32_e32 v25, 0xffff0000, v158
	v_lshlrev_b32_e32 v26, 16, v159
	v_and_b32_e32 v27, 0xffff0000, v159
	v_lshlrev_b32_e32 v28, 16, v160
	v_and_b32_e32 v29, 0xffff0000, v160
	v_lshlrev_b32_e32 v30, 16, v161
	v_and_b32_e32 v31, 0xffff0000, v161
	s_waitcnt vmcnt(6)
	v_lshlrev_b32_e32 v32, 16, v162
	v_and_b32_e32 v33, 0xffff0000, v162
	v_lshlrev_b32_e32 v34, 16, v163
	v_and_b32_e32 v35, 0xffff0000, v163
	v_lshlrev_b32_e32 v36, 16, v164
	v_and_b32_e32 v37, 0xffff0000, v164
	v_lshlrev_b32_e32 v38, 16, v165
	v_and_b32_e32 v39, 0xffff0000, v165
	s_waitcnt vmcnt(5)
	v_lshlrev_b32_e32 v40, 16, v166
	v_and_b32_e32 v41, 0xffff0000, v166
	v_lshlrev_b32_e32 v42, 16, v167
	v_and_b32_e32 v43, 0xffff0000, v167
	v_lshlrev_b32_e32 v44, 16, v168
	v_and_b32_e32 v45, 0xffff0000, v168
	v_lshlrev_b32_e32 v46, 16, v169
	v_and_b32_e32 v47, 0xffff0000, v169
	s_waitcnt vmcnt(4)
	v_lshlrev_b32_e32 v48, 16, v170
	v_and_b32_e32 v49, 0xffff0000, v170
	v_lshlrev_b32_e32 v50, 16, v171
	v_and_b32_e32 v51, 0xffff0000, v171
	v_lshlrev_b32_e32 v52, 16, v172
	v_and_b32_e32 v53, 0xffff0000, v172
	v_lshlrev_b32_e32 v54, 16, v173
	v_and_b32_e32 v55, 0xffff0000, v173
	s_waitcnt vmcnt(3)
	v_lshlrev_b32_e32 v56, 16, v174
	v_and_b32_e32 v57, 0xffff0000, v174
	v_lshlrev_b32_e32 v58, 16, v175
	v_and_b32_e32 v59, 0xffff0000, v175
	v_lshlrev_b32_e32 v60, 16, v176
	v_and_b32_e32 v61, 0xffff0000, v176
	v_lshlrev_b32_e32 v62, 16, v177
	v_and_b32_e32 v63, 0xffff0000, v177
	s_waitcnt vmcnt(2)
	v_lshlrev_b32_e32 v64, 16, v178
	v_and_b32_e32 v65, 0xffff0000, v178
	v_lshlrev_b32_e32 v66, 16, v179
	v_and_b32_e32 v67, 0xffff0000, v179
	v_lshlrev_b32_e32 v68, 16, v180
	v_and_b32_e32 v69, 0xffff0000, v180
	v_lshlrev_b32_e32 v70, 16, v181
	v_and_b32_e32 v71, 0xffff0000, v181
	v_cndmask_b32_e64 v0, v0, 0, s[0:1]
	v_cndmask_b32_e64 v1, v1, 0, s[0:1]
	v_cndmask_b32_e64 v2, v2, 0, s[0:1]
	v_cndmask_b32_e64 v3, v3, 0, s[0:1]
	v_cndmask_b32_e64 v4, v4, 0, s[0:1]
	v_cndmask_b32_e64 v5, v5, 0, s[0:1]
	v_cndmask_b32_e64 v6, v6, 0, s[0:1]
	v_cndmask_b32_e64 v7, v7, 0, s[0:1]
	v_cndmask_b32_e64 v8, v8, 0, s[0:1]
	v_cndmask_b32_e64 v9, v9, 0, s[0:1]
	v_cndmask_b32_e64 v10, v10, 0, s[0:1]
	v_cndmask_b32_e64 v11, v11, 0, s[0:1]
	v_cndmask_b32_e64 v12, v12, 0, s[0:1]
	v_cndmask_b32_e64 v13, v13, 0, s[0:1]
	v_cndmask_b32_e64 v14, v14, 0, s[0:1]
	v_cndmask_b32_e64 v15, v15, 0, s[0:1]
	v_cndmask_b32_e64 v16, v16, 0, s[0:1]
	v_cndmask_b32_e64 v17, v17, 0, s[0:1]
	v_cndmask_b32_e64 v18, v18, 0, s[0:1]
	v_cndmask_b32_e64 v19, v19, 0, s[0:1]
	v_cndmask_b32_e64 v20, v20, 0, s[0:1]
	v_cndmask_b32_e64 v21, v21, 0, s[0:1]
	v_cndmask_b32_e64 v22, v22, 0, s[0:1]
	v_cndmask_b32_e64 v23, v23, 0, s[0:1]
	v_cndmask_b32_e64 v48, v48, 0, s[2:3]
	v_cndmask_b32_e64 v49, v49, 0, s[2:3]
	v_cndmask_b32_e64 v50, v50, 0, s[2:3]
	v_cndmask_b32_e64 v51, v51, 0, s[2:3]
	v_cndmask_b32_e64 v52, v52, 0, s[2:3]
	v_cndmask_b32_e64 v53, v53, 0, s[2:3]
	v_cndmask_b32_e64 v54, v54, 0, s[2:3]
	v_cndmask_b32_e64 v55, v55, 0, s[2:3]
	v_cndmask_b32_e64 v56, v56, 0, s[2:3]
	v_cndmask_b32_e64 v57, v57, 0, s[2:3]
	v_cndmask_b32_e64 v58, v58, 0, s[2:3]
	v_cndmask_b32_e64 v59, v59, 0, s[2:3]
	v_cndmask_b32_e64 v60, v60, 0, s[2:3]
	v_cndmask_b32_e64 v61, v61, 0, s[2:3]
	v_cndmask_b32_e64 v62, v62, 0, s[2:3]
	v_cndmask_b32_e64 v63, v63, 0, s[2:3]
	v_cndmask_b32_e64 v64, v64, 0, s[2:3]
	v_cndmask_b32_e64 v65, v65, 0, s[2:3]
	v_cndmask_b32_e64 v66, v66, 0, s[2:3]
	v_cndmask_b32_e64 v67, v67, 0, s[2:3]
	v_cndmask_b32_e64 v68, v68, 0, s[2:3]
	v_cndmask_b32_e64 v69, v69, 0, s[2:3]
	v_cndmask_b32_e64 v70, v70, 0, s[2:3]
	v_cndmask_b32_e64 v71, v71, 0, s[2:3]
	s_waitcnt vmcnt(0)
	global_load_dwordx4 v[146:149], v136, s[14:15]
	global_load_dwordx4 v[150:153], v137, s[14:15]
	global_load_dwordx4 v[154:157], v138, s[14:15]
	v_add_u32_e32 v136, 0x2c00, v136
	v_add_u32_e32 v137, 0x2c00, v137
	v_add_u32_e32 v138, 0x2c00, v138
	v_subrev_u32_e32 v233, 0x2c00, v136
	v_cndmask_b32_e64 v136, v136, v233, s[4:5]
	v_subrev_u32_e32 v233, 0x2c00, v137
	v_cndmask_b32_e64 v137, v137, v233, s[4:5]
	v_subrev_u32_e32 v233, 0x2c00, v138
	v_cndmask_b32_e64 v138, v138, v233, s[4:5]
	global_load_dwordx4 v[158:161], v136, s[14:15]
	global_load_dwordx4 v[162:165], v137, s[14:15]
	global_load_dwordx4 v[166:169], v138, s[14:15]
	v_add_u32_e32 v136, 0x2c00, v136
	v_add_u32_e32 v137, 0x2c00, v137
	v_add_u32_e32 v138, 0x2c00, v138
	global_load_dwordx4 v[170:173], v136, s[14:15]
	global_load_dwordx4 v[174:177], v137, s[14:15]
	global_load_dwordx4 v[178:181], v138, s[14:15]
	v_add_u32_e32 v136, 0x2c00, v136
	v_add_u32_e32 v137, 0x2c00, v137
	v_add_u32_e32 v138, 0x2c00, v138
	global_load_dwordx4 v[182:185], v136, s[14:15]
	global_load_dwordx4 v[186:189], v137, s[14:15]
	global_load_dwordx4 v[190:193], v138, s[14:15]
	v_add_u32_e32 v136, 0x2c00, v136
	v_add_u32_e32 v137, 0x2c00, v137
	v_add_u32_e32 v138, 0x2c00, v138
	global_load_dwordx4 v[194:197], v136, s[14:15]
	global_load_dwordx4 v[198:201], v137, s[14:15]
	global_load_dwordx4 v[202:205], v138, s[14:15]
	v_add_u32_e32 v136, 0x2c00, v136
	v_add_u32_e32 v137, 0x2c00, v137
	v_add_u32_e32 v138, 0x2c00, v138
	global_load_dwordx4 v[80:83], v139, s[14:15]
	v_add_u32_e32 v139, 0x2c00, v139
	global_load_dwordx4 v[84:87], v139, s[14:15]
	v_add_u32_e32 v139, 0x2c00, v139
	global_load_dwordx4 v[88:91], v139, s[14:15]
	v_add_u32_e32 v139, 0x2c00, v139
	global_load_dwordx4 v[92:95], v139, s[14:15]
	v_add_u32_e32 v139, 0x2c00, v139
	s_waitcnt vmcnt(16)
	v_cndmask_b32_e64 v146, v146, 0, s[4:5]
	v_cndmask_b32_e64 v147, v147, 0, s[4:5]
	v_cndmask_b32_e64 v148, v148, 0, s[4:5]
	v_cndmask_b32_e64 v149, v149, 0, s[4:5]
	v_cndmask_b32_e64 v150, v150, 0, s[4:5]
	v_cndmask_b32_e64 v151, v151, 0, s[4:5]
	v_cndmask_b32_e64 v152, v152, 0, s[4:5]
	v_cndmask_b32_e64 v153, v153, 0, s[4:5]
	v_cndmask_b32_e64 v154, v154, 0, s[4:5]
	v_cndmask_b32_e64 v155, v155, 0, s[4:5]
	v_cndmask_b32_e64 v156, v156, 0, s[4:5]
	v_cndmask_b32_e64 v157, v157, 0, s[4:5]
	global_load_dwordx4 v[206:209], v136, s[14:15]
	global_load_dwordx4 v[210:213], v137, s[14:15]
	global_load_dwordx4 v[214:217], v138, s[14:15]
	v_add_u32_e32 v136, 0x2c00, v136
	v_add_u32_e32 v137, 0x2c00, v137
	v_add_u32_e32 v138, 0x2c00, v138
	global_load_dwordx4 v[96:99], v139, s[14:15]
	v_add_u32_e32 v139, 0x2c00, v139
	s_waitcnt vmcnt(14)
	s_waitcnt vmcnt(7)
	v_mov_b64_e32 v[104:105], v[72:73]
	v_mov_b64_e32 v[106:107], v[74:75]
	v_mov_b64_e32 v[108:109], v[76:77]
	v_mov_b64_e32 v[110:111], v[78:79]
	v_lshlrev_b32_e32 v112, 16, v146
	v_and_b32_e32 v113, 0xffff0000, v146
	v_pk_fma_f32 v[104:105], v[112:113], v[0:1], v[104:105]
	v_lshlrev_b32_e32 v114, 16, v147
	v_and_b32_e32 v115, 0xffff0000, v147
	v_pk_fma_f32 v[106:107], v[114:115], v[2:3], v[106:107]
	v_lshlrev_b32_e32 v112, 16, v148
	v_and_b32_e32 v113, 0xffff0000, v148
	v_pk_fma_f32 v[108:109], v[112:113], v[4:5], v[108:109]
	v_lshlrev_b32_e32 v114, 16, v149
	v_and_b32_e32 v115, 0xffff0000, v149
	v_pk_fma_f32 v[110:111], v[114:115], v[6:7], v[110:111]
	v_lshlrev_b32_e32 v112, 16, v158
	v_and_b32_e32 v113, 0xffff0000, v158
	v_pk_fma_f32 v[104:105], v[112:113], v[8:9], v[104:105]
	v_lshlrev_b32_e32 v114, 16, v159
	v_and_b32_e32 v115, 0xffff0000, v159
	v_pk_fma_f32 v[106:107], v[114:115], v[10:11], v[106:107]
	v_lshlrev_b32_e32 v112, 16, v160
	v_and_b32_e32 v113, 0xffff0000, v160
	v_pk_fma_f32 v[108:109], v[112:113], v[12:13], v[108:109]
	v_lshlrev_b32_e32 v114, 16, v161
	v_and_b32_e32 v115, 0xffff0000, v161
	v_pk_fma_f32 v[110:111], v[114:115], v[14:15], v[110:111]
	v_lshlrev_b32_e32 v112, 16, v170
	v_and_b32_e32 v113, 0xffff0000, v170
	v_pk_fma_f32 v[104:105], v[112:113], v[16:17], v[104:105]
	v_lshlrev_b32_e32 v114, 16, v171
	v_and_b32_e32 v115, 0xffff0000, v171
	v_pk_fma_f32 v[106:107], v[114:115], v[18:19], v[106:107]
	v_lshlrev_b32_e32 v112, 16, v172
	v_and_b32_e32 v113, 0xffff0000, v172
	v_pk_fma_f32 v[108:109], v[112:113], v[20:21], v[108:109]
	v_lshlrev_b32_e32 v114, 16, v173
	v_and_b32_e32 v115, 0xffff0000, v173
	v_pk_fma_f32 v[110:111], v[114:115], v[22:23], v[110:111]
	v_lshlrev_b32_e32 v112, 16, v150
	v_and_b32_e32 v113, 0xffff0000, v150
	v_pk_fma_f32 v[104:105], v[112:113], v[24:25], v[104:105]
	v_lshlrev_b32_e32 v114, 16, v151
	v_and_b32_e32 v115, 0xffff0000, v151
	v_pk_fma_f32 v[106:107], v[114:115], v[26:27], v[106:107]
	v_lshlrev_b32_e32 v112, 16, v152
	v_and_b32_e32 v113, 0xffff0000, v152
	v_pk_fma_f32 v[108:109], v[112:113], v[28:29], v[108:109]
	v_lshlrev_b32_e32 v114, 16, v153
	v_and_b32_e32 v115, 0xffff0000, v153
	v_pk_fma_f32 v[110:111], v[114:115], v[30:31], v[110:111]
	v_lshlrev_b32_e32 v112, 16, v162
	v_and_b32_e32 v113, 0xffff0000, v162
	v_pk_fma_f32 v[104:105], v[112:113], v[32:33], v[104:105]
	v_lshlrev_b32_e32 v114, 16, v163
	v_and_b32_e32 v115, 0xffff0000, v163
	v_pk_fma_f32 v[106:107], v[114:115], v[34:35], v[106:107]
	v_lshlrev_b32_e32 v112, 16, v164
	v_and_b32_e32 v113, 0xffff0000, v164
	v_pk_fma_f32 v[108:109], v[112:113], v[36:37], v[108:109]
	v_lshlrev_b32_e32 v114, 16, v165
	v_and_b32_e32 v115, 0xffff0000, v165
	v_pk_fma_f32 v[110:111], v[114:115], v[38:39], v[110:111]
	v_lshlrev_b32_e32 v112, 16, v174
	v_and_b32_e32 v113, 0xffff0000, v174
	v_pk_fma_f32 v[104:105], v[112:113], v[40:41], v[104:105]
	v_lshlrev_b32_e32 v114, 16, v175
	v_and_b32_e32 v115, 0xffff0000, v175
	v_pk_fma_f32 v[106:107], v[114:115], v[42:43], v[106:107]
	v_lshlrev_b32_e32 v112, 16, v176
	v_and_b32_e32 v113, 0xffff0000, v176
	v_pk_fma_f32 v[108:109], v[112:113], v[44:45], v[108:109]
	v_lshlrev_b32_e32 v114, 16, v177
	v_and_b32_e32 v115, 0xffff0000, v177
	v_pk_fma_f32 v[110:111], v[114:115], v[46:47], v[110:111]
	v_lshlrev_b32_e32 v112, 16, v154
	v_and_b32_e32 v113, 0xffff0000, v154
	v_pk_fma_f32 v[104:105], v[112:113], v[48:49], v[104:105]
	v_lshlrev_b32_e32 v114, 16, v155
	v_and_b32_e32 v115, 0xffff0000, v155
	v_pk_fma_f32 v[106:107], v[114:115], v[50:51], v[106:107]
	v_lshlrev_b32_e32 v112, 16, v156
	v_and_b32_e32 v113, 0xffff0000, v156
	v_pk_fma_f32 v[108:109], v[112:113], v[52:53], v[108:109]
	v_lshlrev_b32_e32 v114, 16, v157
	v_and_b32_e32 v115, 0xffff0000, v157
	v_pk_fma_f32 v[110:111], v[114:115], v[54:55], v[110:111]
	v_lshlrev_b32_e32 v112, 16, v166
	v_and_b32_e32 v113, 0xffff0000, v166
	v_pk_fma_f32 v[104:105], v[112:113], v[56:57], v[104:105]
	v_lshlrev_b32_e32 v114, 16, v167
	v_and_b32_e32 v115, 0xffff0000, v167
	v_pk_fma_f32 v[106:107], v[114:115], v[58:59], v[106:107]
	v_lshlrev_b32_e32 v112, 16, v168
	v_and_b32_e32 v113, 0xffff0000, v168
	v_pk_fma_f32 v[108:109], v[112:113], v[60:61], v[108:109]
	v_lshlrev_b32_e32 v114, 16, v169
	v_and_b32_e32 v115, 0xffff0000, v169
	v_pk_fma_f32 v[110:111], v[114:115], v[62:63], v[110:111]
	v_lshlrev_b32_e32 v112, 16, v178
	v_and_b32_e32 v113, 0xffff0000, v178
	v_pk_fma_f32 v[104:105], v[112:113], v[64:65], v[104:105]
	v_lshlrev_b32_e32 v114, 16, v179
	v_and_b32_e32 v115, 0xffff0000, v179
	v_pk_fma_f32 v[106:107], v[114:115], v[66:67], v[106:107]
	v_lshlrev_b32_e32 v112, 16, v180
	v_and_b32_e32 v113, 0xffff0000, v180
	v_pk_fma_f32 v[108:109], v[112:113], v[68:69], v[108:109]
	v_lshlrev_b32_e32 v114, 16, v181
	v_and_b32_e32 v115, 0xffff0000, v181
	v_pk_fma_f32 v[110:111], v[114:115], v[70:71], v[110:111]
	v_mov_b64_e32 v[132:133], s[28:29]
	v_and_b32_e32 v116, 0x7fffffff, v104
	v_and_b32_e32 v117, 0x7fffffff, v105
	v_pk_fma_f32 v[116:117], v[116:117], s[24:25], 1.0 op_sel_hi:[1,0,0]
	v_pk_mul_f32 v[218:219], v[104:105], v[104:105]
	v_rcp_f32_e32 v116, v116
	v_rcp_f32_e32 v117, v117
	v_pk_mul_f32 v[218:219], v[218:219], s[38:39] op_sel_hi:[1,0]
	v_and_b32_e32 v118, 0x7fffffff, v106
	v_and_b32_e32 v119, 0x7fffffff, v107
	v_pk_fma_f32 v[118:119], v[118:119], s[24:25], 1.0 op_sel_hi:[1,0,0]
	v_pk_mul_f32 v[220:221], v[106:107], v[106:107]
	v_rcp_f32_e32 v118, v118
	v_rcp_f32_e32 v119, v119
	v_pk_mul_f32 v[220:221], v[220:221], s[38:39] op_sel_hi:[1,0]
	v_and_b32_e32 v120, 0x7fffffff, v108
	v_and_b32_e32 v121, 0x7fffffff, v109
	v_pk_fma_f32 v[120:121], v[120:121], s[24:25], 1.0 op_sel_hi:[1,0,0]
	v_pk_mul_f32 v[222:223], v[108:109], v[108:109]
	v_rcp_f32_e32 v120, v120
	v_rcp_f32_e32 v121, v121
	v_pk_mul_f32 v[222:223], v[222:223], s[38:39] op_sel_hi:[1,0]
	v_and_b32_e32 v122, 0x7fffffff, v110
	v_and_b32_e32 v123, 0x7fffffff, v111
	v_pk_fma_f32 v[122:123], v[122:123], s[24:25], 1.0 op_sel_hi:[1,0,0]
	v_pk_mul_f32 v[224:225], v[110:111], v[110:111]
	v_rcp_f32_e32 v122, v122
	v_rcp_f32_e32 v123, v123
	v_pk_mul_f32 v[224:225], v[224:225], s[38:39] op_sel_hi:[1,0]
	v_pk_fma_f32 v[124:125], v[116:117], s[26:27], v[132:133] op_sel_hi:[1,0,0]
	v_exp_f32_e32 v218, v218
	v_pk_fma_f32 v[124:125], v[116:117], v[124:125], s[30:31] op_sel_hi:[1,1,0]
	v_exp_f32_e32 v219, v219
	v_pk_fma_f32 v[124:125], v[116:117], v[124:125], s[34:35] op_sel_hi:[1,1,0]
	v_pk_fma_f32 v[124:125], v[116:117], v[124:125], s[36:37] op_sel_hi:[1,1,0]
	v_pk_mul_f32 v[124:125], v[116:117], v[124:125]
	v_pk_fma_f32 v[126:127], v[118:119], s[26:27], v[132:133] op_sel_hi:[1,0,0]
	v_exp_f32_e32 v220, v220
	v_pk_fma_f32 v[126:127], v[118:119], v[126:127], s[30:31] op_sel_hi:[1,1,0]
	v_exp_f32_e32 v221, v221
	v_pk_fma_f32 v[126:127], v[118:119], v[126:127], s[34:35] op_sel_hi:[1,1,0]
	v_pk_fma_f32 v[126:127], v[118:119], v[126:127], s[36:37] op_sel_hi:[1,1,0]
	v_pk_mul_f32 v[126:127], v[118:119], v[126:127]
	v_pk_fma_f32 v[128:129], v[120:121], s[26:27], v[132:133] op_sel_hi:[1,0,0]
	v_exp_f32_e32 v222, v222
	v_pk_fma_f32 v[128:129], v[120:121], v[128:129], s[30:31] op_sel_hi:[1,1,0]
	v_exp_f32_e32 v223, v223
	v_pk_fma_f32 v[128:129], v[120:121], v[128:129], s[34:35] op_sel_hi:[1,1,0]
	v_pk_fma_f32 v[128:129], v[120:121], v[128:129], s[36:37] op_sel_hi:[1,1,0]
	v_pk_mul_f32 v[128:129], v[120:121], v[128:129]
	v_pk_fma_f32 v[130:131], v[122:123], s[26:27], v[132:133] op_sel_hi:[1,0,0]
	v_exp_f32_e32 v224, v224
	v_pk_fma_f32 v[130:131], v[122:123], v[130:131], s[30:31] op_sel_hi:[1,1,0]
	v_exp_f32_e32 v225, v225
	v_pk_fma_f32 v[130:131], v[122:123], v[130:131], s[34:35] op_sel_hi:[1,1,0]
	v_pk_fma_f32 v[130:131], v[122:123], v[130:131], s[36:37] op_sel_hi:[1,1,0]
	v_pk_mul_f32 v[130:131], v[122:123], v[130:131]
	v_pk_mul_f32 v[124:125], v[218:219], v[124:125]
	v_pk_mul_f32 v[218:219], v[104:105], v[124:125]
	v_pk_fma_f32 v[124:125], v[104:105], v[124:125], v[104:105] neg_lo:[1,0,0] neg_hi:[1,0,0]
	v_cmp_gt_f32_e64 s[8:9], 0, v104
	v_cmp_gt_f32_e64 s[22:23], 0, v105
	v_lshlrev_b32_e32 v112, 16, v80
	v_and_b32_e32 v113, 0xffff0000, v80
	v_cndmask_b32_e64 v104, v124, v218, s[8:9]
	v_cndmask_b32_e64 v105, v125, v219, s[22:23]
	v_pk_mul_f32 v[104:105], v[104:105], v[112:113]
	v_cvt_pk_bf16_f32 v226, v104, v105
	v_pk_mul_f32 v[126:127], v[220:221], v[126:127]
	v_pk_mul_f32 v[220:221], v[106:107], v[126:127]
	v_pk_fma_f32 v[126:127], v[106:107], v[126:127], v[106:107] neg_lo:[1,0,0] neg_hi:[1,0,0]
	v_cmp_gt_f32_e64 s[8:9], 0, v106
	v_cmp_gt_f32_e64 s[22:23], 0, v107
	v_lshlrev_b32_e32 v112, 16, v81
	v_and_b32_e32 v113, 0xffff0000, v81
	v_cndmask_b32_e64 v106, v126, v220, s[8:9]
	v_cndmask_b32_e64 v107, v127, v221, s[22:23]
	v_pk_mul_f32 v[106:107], v[106:107], v[112:113]
	v_cvt_pk_bf16_f32 v227, v106, v107
	v_pk_mul_f32 v[128:129], v[222:223], v[128:129]
	v_pk_mul_f32 v[222:223], v[108:109], v[128:129]
	v_pk_fma_f32 v[128:129], v[108:109], v[128:129], v[108:109] neg_lo:[1,0,0] neg_hi:[1,0,0]
	v_cmp_gt_f32_e64 s[8:9], 0, v108
	v_cmp_gt_f32_e64 s[22:23], 0, v109
	v_lshlrev_b32_e32 v112, 16, v82
	v_and_b32_e32 v113, 0xffff0000, v82
	v_cndmask_b32_e64 v108, v128, v222, s[8:9]
	v_cndmask_b32_e64 v109, v129, v223, s[22:23]
	v_pk_mul_f32 v[108:109], v[108:109], v[112:113]
	v_cvt_pk_bf16_f32 v228, v108, v109
	v_pk_mul_f32 v[130:131], v[224:225], v[130:131]
	v_pk_mul_f32 v[224:225], v[110:111], v[130:131]
	v_pk_fma_f32 v[130:131], v[110:111], v[130:131], v[110:111] neg_lo:[1,0,0] neg_hi:[1,0,0]
	v_cmp_gt_f32_e64 s[8:9], 0, v110
	v_cmp_gt_f32_e64 s[22:23], 0, v111
	v_lshlrev_b32_e32 v112, 16, v83
	v_and_b32_e32 v113, 0xffff0000, v83
	v_cndmask_b32_e64 v110, v130, v224, s[8:9]
	v_cndmask_b32_e64 v111, v131, v225, s[22:23]
	v_pk_mul_f32 v[110:111], v[110:111], v[112:113]
	v_cvt_pk_bf16_f32 v229, v110, v111
	global_store_dwordx4 v140, v[226:229], s[14:15]
	v_add_u32_e32 v140, 0x2c00, v140
	global_load_dwordx4 v[146:149], v136, s[14:15]
	global_load_dwordx4 v[150:153], v137, s[14:15]
	global_load_dwordx4 v[154:157], v138, s[14:15]
	v_add_u32_e32 v136, 0x2c00, v136
	v_add_u32_e32 v137, 0x2c00, v137
	v_add_u32_e32 v138, 0x2c00, v138
	global_load_dwordx4 v[100:103], v139, s[14:15]
	v_add_u32_e32 v139, 0x2c00, v139
	s_waitcnt vmcnt(11)
	v_mov_b64_e32 v[104:105], v[72:73]
	v_mov_b64_e32 v[106:107], v[74:75]
	v_mov_b64_e32 v[108:109], v[76:77]
	v_mov_b64_e32 v[110:111], v[78:79]
	v_lshlrev_b32_e32 v112, 16, v158
	v_and_b32_e32 v113, 0xffff0000, v158
	v_pk_fma_f32 v[104:105], v[112:113], v[0:1], v[104:105]
	v_lshlrev_b32_e32 v114, 16, v159
	v_and_b32_e32 v115, 0xffff0000, v159
	v_pk_fma_f32 v[106:107], v[114:115], v[2:3], v[106:107]
	v_lshlrev_b32_e32 v112, 16, v160
	v_and_b32_e32 v113, 0xffff0000, v160
	v_pk_fma_f32 v[108:109], v[112:113], v[4:5], v[108:109]
	v_lshlrev_b32_e32 v114, 16, v161
	v_and_b32_e32 v115, 0xffff0000, v161
	v_pk_fma_f32 v[110:111], v[114:115], v[6:7], v[110:111]
	v_lshlrev_b32_e32 v112, 16, v170
	v_and_b32_e32 v113, 0xffff0000, v170
	v_pk_fma_f32 v[104:105], v[112:113], v[8:9], v[104:105]
	v_lshlrev_b32_e32 v114, 16, v171
	v_and_b32_e32 v115, 0xffff0000, v171
	v_pk_fma_f32 v[106:107], v[114:115], v[10:11], v[106:107]
	v_lshlrev_b32_e32 v112, 16, v172
	v_and_b32_e32 v113, 0xffff0000, v172
	v_pk_fma_f32 v[108:109], v[112:113], v[12:13], v[108:109]
	v_lshlrev_b32_e32 v114, 16, v173
	v_and_b32_e32 v115, 0xffff0000, v173
	v_pk_fma_f32 v[110:111], v[114:115], v[14:15], v[110:111]
	v_lshlrev_b32_e32 v112, 16, v182
	v_and_b32_e32 v113, 0xffff0000, v182
	v_pk_fma_f32 v[104:105], v[112:113], v[16:17], v[104:105]
	v_lshlrev_b32_e32 v114, 16, v183
	v_and_b32_e32 v115, 0xffff0000, v183
	v_pk_fma_f32 v[106:107], v[114:115], v[18:19], v[106:107]
	v_lshlrev_b32_e32 v112, 16, v184
	v_and_b32_e32 v113, 0xffff0000, v184
	v_pk_fma_f32 v[108:109], v[112:113], v[20:21], v[108:109]
	v_lshlrev_b32_e32 v114, 16, v185
	v_and_b32_e32 v115, 0xffff0000, v185
	v_pk_fma_f32 v[110:111], v[114:115], v[22:23], v[110:111]
	v_lshlrev_b32_e32 v112, 16, v162
	v_and_b32_e32 v113, 0xffff0000, v162
	v_pk_fma_f32 v[104:105], v[112:113], v[24:25], v[104:105]
	v_lshlrev_b32_e32 v114, 16, v163
	v_and_b32_e32 v115, 0xffff0000, v163
	v_pk_fma_f32 v[106:107], v[114:115], v[26:27], v[106:107]
	v_lshlrev_b32_e32 v112, 16, v164
	v_and_b32_e32 v113, 0xffff0000, v164
	v_pk_fma_f32 v[108:109], v[112:113], v[28:29], v[108:109]
	v_lshlrev_b32_e32 v114, 16, v165
	v_and_b32_e32 v115, 0xffff0000, v165
	v_pk_fma_f32 v[110:111], v[114:115], v[30:31], v[110:111]
	v_lshlrev_b32_e32 v112, 16, v174
	v_and_b32_e32 v113, 0xffff0000, v174
	v_pk_fma_f32 v[104:105], v[112:113], v[32:33], v[104:105]
	v_lshlrev_b32_e32 v114, 16, v175
	v_and_b32_e32 v115, 0xffff0000, v175
	v_pk_fma_f32 v[106:107], v[114:115], v[34:35], v[106:107]
	v_lshlrev_b32_e32 v112, 16, v176
	v_and_b32_e32 v113, 0xffff0000, v176
	v_pk_fma_f32 v[108:109], v[112:113], v[36:37], v[108:109]
	v_lshlrev_b32_e32 v114, 16, v177
	v_and_b32_e32 v115, 0xffff0000, v177
	v_pk_fma_f32 v[110:111], v[114:115], v[38:39], v[110:111]
	v_lshlrev_b32_e32 v112, 16, v186
	v_and_b32_e32 v113, 0xffff0000, v186
	v_pk_fma_f32 v[104:105], v[112:113], v[40:41], v[104:105]
	v_lshlrev_b32_e32 v114, 16, v187
	v_and_b32_e32 v115, 0xffff0000, v187
	v_pk_fma_f32 v[106:107], v[114:115], v[42:43], v[106:107]
	v_lshlrev_b32_e32 v112, 16, v188
	v_and_b32_e32 v113, 0xffff0000, v188
	v_pk_fma_f32 v[108:109], v[112:113], v[44:45], v[108:109]
	v_lshlrev_b32_e32 v114, 16, v189
	v_and_b32_e32 v115, 0xffff0000, v189
	v_pk_fma_f32 v[110:111], v[114:115], v[46:47], v[110:111]
	v_lshlrev_b32_e32 v112, 16, v166
	v_and_b32_e32 v113, 0xffff0000, v166
	v_pk_fma_f32 v[104:105], v[112:113], v[48:49], v[104:105]
	v_lshlrev_b32_e32 v114, 16, v167
	v_and_b32_e32 v115, 0xffff0000, v167
	v_pk_fma_f32 v[106:107], v[114:115], v[50:51], v[106:107]
	v_lshlrev_b32_e32 v112, 16, v168
	v_and_b32_e32 v113, 0xffff0000, v168
	v_pk_fma_f32 v[108:109], v[112:113], v[52:53], v[108:109]
	v_lshlrev_b32_e32 v114, 16, v169
	v_and_b32_e32 v115, 0xffff0000, v169
	v_pk_fma_f32 v[110:111], v[114:115], v[54:55], v[110:111]
	v_lshlrev_b32_e32 v112, 16, v178
	v_and_b32_e32 v113, 0xffff0000, v178
	v_pk_fma_f32 v[104:105], v[112:113], v[56:57], v[104:105]
	v_lshlrev_b32_e32 v114, 16, v179
	v_and_b32_e32 v115, 0xffff0000, v179
	v_pk_fma_f32 v[106:107], v[114:115], v[58:59], v[106:107]
	v_lshlrev_b32_e32 v112, 16, v180
	v_and_b32_e32 v113, 0xffff0000, v180
	v_pk_fma_f32 v[108:109], v[112:113], v[60:61], v[108:109]
	v_lshlrev_b32_e32 v114, 16, v181
	v_and_b32_e32 v115, 0xffff0000, v181
	v_pk_fma_f32 v[110:111], v[114:115], v[62:63], v[110:111]
	v_lshlrev_b32_e32 v112, 16, v190
	v_and_b32_e32 v113, 0xffff0000, v190
	v_pk_fma_f32 v[104:105], v[112:113], v[64:65], v[104:105]
	v_lshlrev_b32_e32 v114, 16, v191
	v_and_b32_e32 v115, 0xffff0000, v191
	v_pk_fma_f32 v[106:107], v[114:115], v[66:67], v[106:107]
	v_lshlrev_b32_e32 v112, 16, v192
	v_and_b32_e32 v113, 0xffff0000, v192
	v_pk_fma_f32 v[108:109], v[112:113], v[68:69], v[108:109]
	v_lshlrev_b32_e32 v114, 16, v193
	v_and_b32_e32 v115, 0xffff0000, v193
	v_pk_fma_f32 v[110:111], v[114:115], v[70:71], v[110:111]
	v_mov_b64_e32 v[132:133], s[28:29]
	v_and_b32_e32 v116, 0x7fffffff, v104
	v_and_b32_e32 v117, 0x7fffffff, v105
	v_pk_fma_f32 v[116:117], v[116:117], s[24:25], 1.0 op_sel_hi:[1,0,0]
	v_pk_mul_f32 v[218:219], v[104:105], v[104:105]
	v_rcp_f32_e32 v116, v116
	v_rcp_f32_e32 v117, v117
	v_pk_mul_f32 v[218:219], v[218:219], s[38:39] op_sel_hi:[1,0]
	v_and_b32_e32 v118, 0x7fffffff, v106
	v_and_b32_e32 v119, 0x7fffffff, v107
	v_pk_fma_f32 v[118:119], v[118:119], s[24:25], 1.0 op_sel_hi:[1,0,0]
	v_pk_mul_f32 v[220:221], v[106:107], v[106:107]
	v_rcp_f32_e32 v118, v118
	v_rcp_f32_e32 v119, v119
	v_pk_mul_f32 v[220:221], v[220:221], s[38:39] op_sel_hi:[1,0]
	v_and_b32_e32 v120, 0x7fffffff, v108
	v_and_b32_e32 v121, 0x7fffffff, v109
	v_pk_fma_f32 v[120:121], v[120:121], s[24:25], 1.0 op_sel_hi:[1,0,0]
	v_pk_mul_f32 v[222:223], v[108:109], v[108:109]
	v_rcp_f32_e32 v120, v120
	v_rcp_f32_e32 v121, v121
	v_pk_mul_f32 v[222:223], v[222:223], s[38:39] op_sel_hi:[1,0]
	v_and_b32_e32 v122, 0x7fffffff, v110
	v_and_b32_e32 v123, 0x7fffffff, v111
	v_pk_fma_f32 v[122:123], v[122:123], s[24:25], 1.0 op_sel_hi:[1,0,0]
	v_pk_mul_f32 v[224:225], v[110:111], v[110:111]
	v_rcp_f32_e32 v122, v122
	v_rcp_f32_e32 v123, v123
	v_pk_mul_f32 v[224:225], v[224:225], s[38:39] op_sel_hi:[1,0]
	v_pk_fma_f32 v[124:125], v[116:117], s[26:27], v[132:133] op_sel_hi:[1,0,0]
	v_exp_f32_e32 v218, v218
	v_pk_fma_f32 v[124:125], v[116:117], v[124:125], s[30:31] op_sel_hi:[1,1,0]
	v_exp_f32_e32 v219, v219
	v_pk_fma_f32 v[124:125], v[116:117], v[124:125], s[34:35] op_sel_hi:[1,1,0]
	v_pk_fma_f32 v[124:125], v[116:117], v[124:125], s[36:37] op_sel_hi:[1,1,0]
	v_pk_mul_f32 v[124:125], v[116:117], v[124:125]
	v_pk_fma_f32 v[126:127], v[118:119], s[26:27], v[132:133] op_sel_hi:[1,0,0]
	v_exp_f32_e32 v220, v220
	v_pk_fma_f32 v[126:127], v[118:119], v[126:127], s[30:31] op_sel_hi:[1,1,0]
	v_exp_f32_e32 v221, v221
	v_pk_fma_f32 v[126:127], v[118:119], v[126:127], s[34:35] op_sel_hi:[1,1,0]
	v_pk_fma_f32 v[126:127], v[118:119], v[126:127], s[36:37] op_sel_hi:[1,1,0]
	v_pk_mul_f32 v[126:127], v[118:119], v[126:127]
	v_pk_fma_f32 v[128:129], v[120:121], s[26:27], v[132:133] op_sel_hi:[1,0,0]
	v_exp_f32_e32 v222, v222
	v_pk_fma_f32 v[128:129], v[120:121], v[128:129], s[30:31] op_sel_hi:[1,1,0]
	v_exp_f32_e32 v223, v223
	v_pk_fma_f32 v[128:129], v[120:121], v[128:129], s[34:35] op_sel_hi:[1,1,0]
	v_pk_fma_f32 v[128:129], v[120:121], v[128:129], s[36:37] op_sel_hi:[1,1,0]
	v_pk_mul_f32 v[128:129], v[120:121], v[128:129]
	v_pk_fma_f32 v[130:131], v[122:123], s[26:27], v[132:133] op_sel_hi:[1,0,0]
	v_exp_f32_e32 v224, v224
	v_pk_fma_f32 v[130:131], v[122:123], v[130:131], s[30:31] op_sel_hi:[1,1,0]
	v_exp_f32_e32 v225, v225
	v_pk_fma_f32 v[130:131], v[122:123], v[130:131], s[34:35] op_sel_hi:[1,1,0]
	v_pk_fma_f32 v[130:131], v[122:123], v[130:131], s[36:37] op_sel_hi:[1,1,0]
	v_pk_mul_f32 v[130:131], v[122:123], v[130:131]
	v_pk_mul_f32 v[124:125], v[218:219], v[124:125]
	v_pk_mul_f32 v[218:219], v[104:105], v[124:125]
	v_pk_fma_f32 v[124:125], v[104:105], v[124:125], v[104:105] neg_lo:[1,0,0] neg_hi:[1,0,0]
	v_cmp_gt_f32_e64 s[8:9], 0, v104
	v_cmp_gt_f32_e64 s[22:23], 0, v105
	v_lshlrev_b32_e32 v112, 16, v84
	v_and_b32_e32 v113, 0xffff0000, v84
	v_cndmask_b32_e64 v104, v124, v218, s[8:9]
	v_cndmask_b32_e64 v105, v125, v219, s[22:23]
	v_pk_mul_f32 v[104:105], v[104:105], v[112:113]
	v_cvt_pk_bf16_f32 v226, v104, v105
	v_pk_mul_f32 v[126:127], v[220:221], v[126:127]
	v_pk_mul_f32 v[220:221], v[106:107], v[126:127]
	v_pk_fma_f32 v[126:127], v[106:107], v[126:127], v[106:107] neg_lo:[1,0,0] neg_hi:[1,0,0]
	v_cmp_gt_f32_e64 s[8:9], 0, v106
	v_cmp_gt_f32_e64 s[22:23], 0, v107
	v_lshlrev_b32_e32 v112, 16, v85
	v_and_b32_e32 v113, 0xffff0000, v85
	v_cndmask_b32_e64 v106, v126, v220, s[8:9]
	v_cndmask_b32_e64 v107, v127, v221, s[22:23]
	v_pk_mul_f32 v[106:107], v[106:107], v[112:113]
	v_cvt_pk_bf16_f32 v227, v106, v107
	v_pk_mul_f32 v[128:129], v[222:223], v[128:129]
	v_pk_mul_f32 v[222:223], v[108:109], v[128:129]
	v_pk_fma_f32 v[128:129], v[108:109], v[128:129], v[108:109] neg_lo:[1,0,0] neg_hi:[1,0,0]
	v_cmp_gt_f32_e64 s[8:9], 0, v108
	v_cmp_gt_f32_e64 s[22:23], 0, v109
	v_lshlrev_b32_e32 v112, 16, v86
	v_and_b32_e32 v113, 0xffff0000, v86
	v_cndmask_b32_e64 v108, v128, v222, s[8:9]
	v_cndmask_b32_e64 v109, v129, v223, s[22:23]
	v_pk_mul_f32 v[108:109], v[108:109], v[112:113]
	v_cvt_pk_bf16_f32 v228, v108, v109
	v_pk_mul_f32 v[130:131], v[224:225], v[130:131]
	v_pk_mul_f32 v[224:225], v[110:111], v[130:131]
	v_pk_fma_f32 v[130:131], v[110:111], v[130:131], v[110:111] neg_lo:[1,0,0] neg_hi:[1,0,0]
	v_cmp_gt_f32_e64 s[8:9], 0, v110
	v_cmp_gt_f32_e64 s[22:23], 0, v111
	v_lshlrev_b32_e32 v112, 16, v87
	v_and_b32_e32 v113, 0xffff0000, v87
	v_cndmask_b32_e64 v110, v130, v224, s[8:9]
	v_cndmask_b32_e64 v111, v131, v225, s[22:23]
	v_pk_mul_f32 v[110:111], v[110:111], v[112:113]
	v_cvt_pk_bf16_f32 v229, v110, v111
	global_store_dwordx4 v140, v[226:229], s[14:15]
	v_add_u32_e32 v140, 0x2c00, v140
	global_load_dwordx4 v[158:161], v136, s[14:15]
	global_load_dwordx4 v[162:165], v137, s[14:15]
	global_load_dwordx4 v[166:169], v138, s[14:15]
	v_add_u32_e32 v136, 0x2c00, v136
	v_add_u32_e32 v137, 0x2c00, v137
	v_add_u32_e32 v138, 0x2c00, v138
	global_load_dwordx4 v[80:83], v139, s[14:15]
	v_add_u32_e32 v139, 0x2c00, v139
	s_waitcnt vmcnt(15)
	v_mov_b64_e32 v[104:105], v[72:73]
	v_mov_b64_e32 v[106:107], v[74:75]
	v_mov_b64_e32 v[108:109], v[76:77]
	v_mov_b64_e32 v[110:111], v[78:79]
	v_lshlrev_b32_e32 v112, 16, v170
	v_and_b32_e32 v113, 0xffff0000, v170
	v_pk_fma_f32 v[104:105], v[112:113], v[0:1], v[104:105]
	v_lshlrev_b32_e32 v114, 16, v171
	v_and_b32_e32 v115, 0xffff0000, v171
	v_pk_fma_f32 v[106:107], v[114:115], v[2:3], v[106:107]
	v_lshlrev_b32_e32 v112, 16, v172
	v_and_b32_e32 v113, 0xffff0000, v172
	v_pk_fma_f32 v[108:109], v[112:113], v[4:5], v[108:109]
	v_lshlrev_b32_e32 v114, 16, v173
	v_and_b32_e32 v115, 0xffff0000, v173
	v_pk_fma_f32 v[110:111], v[114:115], v[6:7], v[110:111]
	v_lshlrev_b32_e32 v112, 16, v182
	v_and_b32_e32 v113, 0xffff0000, v182
	v_pk_fma_f32 v[104:105], v[112:113], v[8:9], v[104:105]
	v_lshlrev_b32_e32 v114, 16, v183
	v_and_b32_e32 v115, 0xffff0000, v183
	v_pk_fma_f32 v[106:107], v[114:115], v[10:11], v[106:107]
	v_lshlrev_b32_e32 v112, 16, v184
	v_and_b32_e32 v113, 0xffff0000, v184
	v_pk_fma_f32 v[108:109], v[112:113], v[12:13], v[108:109]
	v_lshlrev_b32_e32 v114, 16, v185
	v_and_b32_e32 v115, 0xffff0000, v185
	v_pk_fma_f32 v[110:111], v[114:115], v[14:15], v[110:111]
	v_lshlrev_b32_e32 v112, 16, v194
	v_and_b32_e32 v113, 0xffff0000, v194
	v_pk_fma_f32 v[104:105], v[112:113], v[16:17], v[104:105]
	v_lshlrev_b32_e32 v114, 16, v195
	v_and_b32_e32 v115, 0xffff0000, v195
	v_pk_fma_f32 v[106:107], v[114:115], v[18:19], v[106:107]
	v_lshlrev_b32_e32 v112, 16, v196
	v_and_b32_e32 v113, 0xffff0000, v196
	v_pk_fma_f32 v[108:109], v[112:113], v[20:21], v[108:109]
	v_lshlrev_b32_e32 v114, 16, v197
	v_and_b32_e32 v115, 0xffff0000, v197
	v_pk_fma_f32 v[110:111], v[114:115], v[22:23], v[110:111]
	v_lshlrev_b32_e32 v112, 16, v174
	v_and_b32_e32 v113, 0xffff0000, v174
	v_pk_fma_f32 v[104:105], v[112:113], v[24:25], v[104:105]
	v_lshlrev_b32_e32 v114, 16, v175
	v_and_b32_e32 v115, 0xffff0000, v175
	v_pk_fma_f32 v[106:107], v[114:115], v[26:27], v[106:107]
	v_lshlrev_b32_e32 v112, 16, v176
	v_and_b32_e32 v113, 0xffff0000, v176
	v_pk_fma_f32 v[108:109], v[112:113], v[28:29], v[108:109]
	v_lshlrev_b32_e32 v114, 16, v177
	v_and_b32_e32 v115, 0xffff0000, v177
	v_pk_fma_f32 v[110:111], v[114:115], v[30:31], v[110:111]
	v_lshlrev_b32_e32 v112, 16, v186
	v_and_b32_e32 v113, 0xffff0000, v186
	v_pk_fma_f32 v[104:105], v[112:113], v[32:33], v[104:105]
	v_lshlrev_b32_e32 v114, 16, v187
	v_and_b32_e32 v115, 0xffff0000, v187
	v_pk_fma_f32 v[106:107], v[114:115], v[34:35], v[106:107]
	v_lshlrev_b32_e32 v112, 16, v188
	v_and_b32_e32 v113, 0xffff0000, v188
	v_pk_fma_f32 v[108:109], v[112:113], v[36:37], v[108:109]
	v_lshlrev_b32_e32 v114, 16, v189
	v_and_b32_e32 v115, 0xffff0000, v189
	v_pk_fma_f32 v[110:111], v[114:115], v[38:39], v[110:111]
	v_lshlrev_b32_e32 v112, 16, v198
	v_and_b32_e32 v113, 0xffff0000, v198
	v_pk_fma_f32 v[104:105], v[112:113], v[40:41], v[104:105]
	v_lshlrev_b32_e32 v114, 16, v199
	v_and_b32_e32 v115, 0xffff0000, v199
	v_pk_fma_f32 v[106:107], v[114:115], v[42:43], v[106:107]
	v_lshlrev_b32_e32 v112, 16, v200
	v_and_b32_e32 v113, 0xffff0000, v200
	v_pk_fma_f32 v[108:109], v[112:113], v[44:45], v[108:109]
	v_lshlrev_b32_e32 v114, 16, v201
	v_and_b32_e32 v115, 0xffff0000, v201
	v_pk_fma_f32 v[110:111], v[114:115], v[46:47], v[110:111]
	v_lshlrev_b32_e32 v112, 16, v178
	v_and_b32_e32 v113, 0xffff0000, v178
	v_pk_fma_f32 v[104:105], v[112:113], v[48:49], v[104:105]
	v_lshlrev_b32_e32 v114, 16, v179
	v_and_b32_e32 v115, 0xffff0000, v179
	v_pk_fma_f32 v[106:107], v[114:115], v[50:51], v[106:107]
	v_lshlrev_b32_e32 v112, 16, v180
	v_and_b32_e32 v113, 0xffff0000, v180
	v_pk_fma_f32 v[108:109], v[112:113], v[52:53], v[108:109]
	v_lshlrev_b32_e32 v114, 16, v181
	v_and_b32_e32 v115, 0xffff0000, v181
	v_pk_fma_f32 v[110:111], v[114:115], v[54:55], v[110:111]
	v_lshlrev_b32_e32 v112, 16, v190
	v_and_b32_e32 v113, 0xffff0000, v190
	v_pk_fma_f32 v[104:105], v[112:113], v[56:57], v[104:105]
	v_lshlrev_b32_e32 v114, 16, v191
	v_and_b32_e32 v115, 0xffff0000, v191
	v_pk_fma_f32 v[106:107], v[114:115], v[58:59], v[106:107]
	v_lshlrev_b32_e32 v112, 16, v192
	v_and_b32_e32 v113, 0xffff0000, v192
	v_pk_fma_f32 v[108:109], v[112:113], v[60:61], v[108:109]
	v_lshlrev_b32_e32 v114, 16, v193
	v_and_b32_e32 v115, 0xffff0000, v193
	v_pk_fma_f32 v[110:111], v[114:115], v[62:63], v[110:111]
	v_lshlrev_b32_e32 v112, 16, v202
	v_and_b32_e32 v113, 0xffff0000, v202
	v_pk_fma_f32 v[104:105], v[112:113], v[64:65], v[104:105]
	v_lshlrev_b32_e32 v114, 16, v203
	v_and_b32_e32 v115, 0xffff0000, v203
	v_pk_fma_f32 v[106:107], v[114:115], v[66:67], v[106:107]
	v_lshlrev_b32_e32 v112, 16, v204
	v_and_b32_e32 v113, 0xffff0000, v204
	v_pk_fma_f32 v[108:109], v[112:113], v[68:69], v[108:109]
	v_lshlrev_b32_e32 v114, 16, v205
	v_and_b32_e32 v115, 0xffff0000, v205
	v_pk_fma_f32 v[110:111], v[114:115], v[70:71], v[110:111]
	v_mov_b64_e32 v[132:133], s[28:29]
	v_and_b32_e32 v116, 0x7fffffff, v104
	v_and_b32_e32 v117, 0x7fffffff, v105
	v_pk_fma_f32 v[116:117], v[116:117], s[24:25], 1.0 op_sel_hi:[1,0,0]
	v_pk_mul_f32 v[218:219], v[104:105], v[104:105]
	v_rcp_f32_e32 v116, v116
	v_rcp_f32_e32 v117, v117
	v_pk_mul_f32 v[218:219], v[218:219], s[38:39] op_sel_hi:[1,0]
	v_and_b32_e32 v118, 0x7fffffff, v106
	v_and_b32_e32 v119, 0x7fffffff, v107
	v_pk_fma_f32 v[118:119], v[118:119], s[24:25], 1.0 op_sel_hi:[1,0,0]
	v_pk_mul_f32 v[220:221], v[106:107], v[106:107]
	v_rcp_f32_e32 v118, v118
	v_rcp_f32_e32 v119, v119
	v_pk_mul_f32 v[220:221], v[220:221], s[38:39] op_sel_hi:[1,0]
	v_and_b32_e32 v120, 0x7fffffff, v108
	v_and_b32_e32 v121, 0x7fffffff, v109
	v_pk_fma_f32 v[120:121], v[120:121], s[24:25], 1.0 op_sel_hi:[1,0,0]
	v_pk_mul_f32 v[222:223], v[108:109], v[108:109]
	v_rcp_f32_e32 v120, v120
	v_rcp_f32_e32 v121, v121
	v_pk_mul_f32 v[222:223], v[222:223], s[38:39] op_sel_hi:[1,0]
	v_and_b32_e32 v122, 0x7fffffff, v110
	v_and_b32_e32 v123, 0x7fffffff, v111
	v_pk_fma_f32 v[122:123], v[122:123], s[24:25], 1.0 op_sel_hi:[1,0,0]
	v_pk_mul_f32 v[224:225], v[110:111], v[110:111]
	v_rcp_f32_e32 v122, v122
	v_rcp_f32_e32 v123, v123
	v_pk_mul_f32 v[224:225], v[224:225], s[38:39] op_sel_hi:[1,0]
	v_pk_fma_f32 v[124:125], v[116:117], s[26:27], v[132:133] op_sel_hi:[1,0,0]
	v_exp_f32_e32 v218, v218
	v_pk_fma_f32 v[124:125], v[116:117], v[124:125], s[30:31] op_sel_hi:[1,1,0]
	v_exp_f32_e32 v219, v219
	v_pk_fma_f32 v[124:125], v[116:117], v[124:125], s[34:35] op_sel_hi:[1,1,0]
	v_pk_fma_f32 v[124:125], v[116:117], v[124:125], s[36:37] op_sel_hi:[1,1,0]
	v_pk_mul_f32 v[124:125], v[116:117], v[124:125]
	v_pk_fma_f32 v[126:127], v[118:119], s[26:27], v[132:133] op_sel_hi:[1,0,0]
	v_exp_f32_e32 v220, v220
	v_pk_fma_f32 v[126:127], v[118:119], v[126:127], s[30:31] op_sel_hi:[1,1,0]
	v_exp_f32_e32 v221, v221
	v_pk_fma_f32 v[126:127], v[118:119], v[126:127], s[34:35] op_sel_hi:[1,1,0]
	v_pk_fma_f32 v[126:127], v[118:119], v[126:127], s[36:37] op_sel_hi:[1,1,0]
	v_pk_mul_f32 v[126:127], v[118:119], v[126:127]
	v_pk_fma_f32 v[128:129], v[120:121], s[26:27], v[132:133] op_sel_hi:[1,0,0]
	v_exp_f32_e32 v222, v222
	v_pk_fma_f32 v[128:129], v[120:121], v[128:129], s[30:31] op_sel_hi:[1,1,0]
	v_exp_f32_e32 v223, v223
	v_pk_fma_f32 v[128:129], v[120:121], v[128:129], s[34:35] op_sel_hi:[1,1,0]
	v_pk_fma_f32 v[128:129], v[120:121], v[128:129], s[36:37] op_sel_hi:[1,1,0]
	v_pk_mul_f32 v[128:129], v[120:121], v[128:129]
	v_pk_fma_f32 v[130:131], v[122:123], s[26:27], v[132:133] op_sel_hi:[1,0,0]
	v_exp_f32_e32 v224, v224
	v_pk_fma_f32 v[130:131], v[122:123], v[130:131], s[30:31] op_sel_hi:[1,1,0]
	v_exp_f32_e32 v225, v225
	v_pk_fma_f32 v[130:131], v[122:123], v[130:131], s[34:35] op_sel_hi:[1,1,0]
	v_pk_fma_f32 v[130:131], v[122:123], v[130:131], s[36:37] op_sel_hi:[1,1,0]
	v_pk_mul_f32 v[130:131], v[122:123], v[130:131]
	v_pk_mul_f32 v[124:125], v[218:219], v[124:125]
	v_pk_mul_f32 v[218:219], v[104:105], v[124:125]
	v_pk_fma_f32 v[124:125], v[104:105], v[124:125], v[104:105] neg_lo:[1,0,0] neg_hi:[1,0,0]
	v_cmp_gt_f32_e64 s[8:9], 0, v104
	v_cmp_gt_f32_e64 s[22:23], 0, v105
	v_lshlrev_b32_e32 v112, 16, v88
	v_and_b32_e32 v113, 0xffff0000, v88
	v_cndmask_b32_e64 v104, v124, v218, s[8:9]
	v_cndmask_b32_e64 v105, v125, v219, s[22:23]
	v_pk_mul_f32 v[104:105], v[104:105], v[112:113]
	v_cvt_pk_bf16_f32 v226, v104, v105
	v_pk_mul_f32 v[126:127], v[220:221], v[126:127]
	v_pk_mul_f32 v[220:221], v[106:107], v[126:127]
	v_pk_fma_f32 v[126:127], v[106:107], v[126:127], v[106:107] neg_lo:[1,0,0] neg_hi:[1,0,0]
	v_cmp_gt_f32_e64 s[8:9], 0, v106
	v_cmp_gt_f32_e64 s[22:23], 0, v107
	v_lshlrev_b32_e32 v112, 16, v89
	v_and_b32_e32 v113, 0xffff0000, v89
	v_cndmask_b32_e64 v106, v126, v220, s[8:9]
	v_cndmask_b32_e64 v107, v127, v221, s[22:23]
	v_pk_mul_f32 v[106:107], v[106:107], v[112:113]
	v_cvt_pk_bf16_f32 v227, v106, v107
	v_pk_mul_f32 v[128:129], v[222:223], v[128:129]
	v_pk_mul_f32 v[222:223], v[108:109], v[128:129]
	v_pk_fma_f32 v[128:129], v[108:109], v[128:129], v[108:109] neg_lo:[1,0,0] neg_hi:[1,0,0]
	v_cmp_gt_f32_e64 s[8:9], 0, v108
	v_cmp_gt_f32_e64 s[22:23], 0, v109
	v_lshlrev_b32_e32 v112, 16, v90
	v_and_b32_e32 v113, 0xffff0000, v90
	v_cndmask_b32_e64 v108, v128, v222, s[8:9]
	v_cndmask_b32_e64 v109, v129, v223, s[22:23]
	v_pk_mul_f32 v[108:109], v[108:109], v[112:113]
	v_cvt_pk_bf16_f32 v228, v108, v109
	v_pk_mul_f32 v[130:131], v[224:225], v[130:131]
	v_pk_mul_f32 v[224:225], v[110:111], v[130:131]
	v_pk_fma_f32 v[130:131], v[110:111], v[130:131], v[110:111] neg_lo:[1,0,0] neg_hi:[1,0,0]
	v_cmp_gt_f32_e64 s[8:9], 0, v110
	v_cmp_gt_f32_e64 s[22:23], 0, v111
	v_lshlrev_b32_e32 v112, 16, v91
	v_and_b32_e32 v113, 0xffff0000, v91
	v_cndmask_b32_e64 v110, v130, v224, s[8:9]
	v_cndmask_b32_e64 v111, v131, v225, s[22:23]
	v_pk_mul_f32 v[110:111], v[110:111], v[112:113]
	v_cvt_pk_bf16_f32 v229, v110, v111
	global_store_dwordx4 v140, v[226:229], s[14:15]
	v_add_u32_e32 v140, 0x2c00, v140
	global_load_dwordx4 v[170:173], v136, s[14:15]
	global_load_dwordx4 v[174:177], v137, s[14:15]
	global_load_dwordx4 v[178:181], v138, s[14:15]
	v_add_u32_e32 v136, 0x2c00, v136
	v_add_u32_e32 v137, 0x2c00, v137
	v_add_u32_e32 v138, 0x2c00, v138
	global_load_dwordx4 v[84:87], v139, s[14:15]
	v_add_u32_e32 v139, 0x2c00, v139
	s_waitcnt vmcnt(16)
	v_mov_b64_e32 v[104:105], v[72:73]
	v_mov_b64_e32 v[106:107], v[74:75]
	v_mov_b64_e32 v[108:109], v[76:77]
	v_mov_b64_e32 v[110:111], v[78:79]
	v_lshlrev_b32_e32 v112, 16, v182
	v_and_b32_e32 v113, 0xffff0000, v182
	v_pk_fma_f32 v[104:105], v[112:113], v[0:1], v[104:105]
	v_lshlrev_b32_e32 v114, 16, v183
	v_and_b32_e32 v115, 0xffff0000, v183
	v_pk_fma_f32 v[106:107], v[114:115], v[2:3], v[106:107]
	v_lshlrev_b32_e32 v112, 16, v184
	v_and_b32_e32 v113, 0xffff0000, v184
	v_pk_fma_f32 v[108:109], v[112:113], v[4:5], v[108:109]
	v_lshlrev_b32_e32 v114, 16, v185
	v_and_b32_e32 v115, 0xffff0000, v185
	v_pk_fma_f32 v[110:111], v[114:115], v[6:7], v[110:111]
	v_lshlrev_b32_e32 v112, 16, v194
	v_and_b32_e32 v113, 0xffff0000, v194
	v_pk_fma_f32 v[104:105], v[112:113], v[8:9], v[104:105]
	v_lshlrev_b32_e32 v114, 16, v195
	v_and_b32_e32 v115, 0xffff0000, v195
	v_pk_fma_f32 v[106:107], v[114:115], v[10:11], v[106:107]
	v_lshlrev_b32_e32 v112, 16, v196
	v_and_b32_e32 v113, 0xffff0000, v196
	v_pk_fma_f32 v[108:109], v[112:113], v[12:13], v[108:109]
	v_lshlrev_b32_e32 v114, 16, v197
	v_and_b32_e32 v115, 0xffff0000, v197
	v_pk_fma_f32 v[110:111], v[114:115], v[14:15], v[110:111]
	v_lshlrev_b32_e32 v112, 16, v206
	v_and_b32_e32 v113, 0xffff0000, v206
	v_pk_fma_f32 v[104:105], v[112:113], v[16:17], v[104:105]
	v_lshlrev_b32_e32 v114, 16, v207
	v_and_b32_e32 v115, 0xffff0000, v207
	v_pk_fma_f32 v[106:107], v[114:115], v[18:19], v[106:107]
	v_lshlrev_b32_e32 v112, 16, v208
	v_and_b32_e32 v113, 0xffff0000, v208
	v_pk_fma_f32 v[108:109], v[112:113], v[20:21], v[108:109]
	v_lshlrev_b32_e32 v114, 16, v209
	v_and_b32_e32 v115, 0xffff0000, v209
	v_pk_fma_f32 v[110:111], v[114:115], v[22:23], v[110:111]
	v_lshlrev_b32_e32 v112, 16, v186
	v_and_b32_e32 v113, 0xffff0000, v186
	v_pk_fma_f32 v[104:105], v[112:113], v[24:25], v[104:105]
	v_lshlrev_b32_e32 v114, 16, v187
	v_and_b32_e32 v115, 0xffff0000, v187
	v_pk_fma_f32 v[106:107], v[114:115], v[26:27], v[106:107]
	v_lshlrev_b32_e32 v112, 16, v188
	v_and_b32_e32 v113, 0xffff0000, v188
	v_pk_fma_f32 v[108:109], v[112:113], v[28:29], v[108:109]
	v_lshlrev_b32_e32 v114, 16, v189
	v_and_b32_e32 v115, 0xffff0000, v189
	v_pk_fma_f32 v[110:111], v[114:115], v[30:31], v[110:111]
	v_lshlrev_b32_e32 v112, 16, v198
	v_and_b32_e32 v113, 0xffff0000, v198
	v_pk_fma_f32 v[104:105], v[112:113], v[32:33], v[104:105]
	v_lshlrev_b32_e32 v114, 16, v199
	v_and_b32_e32 v115, 0xffff0000, v199
	v_pk_fma_f32 v[106:107], v[114:115], v[34:35], v[106:107]
	v_lshlrev_b32_e32 v112, 16, v200
	v_and_b32_e32 v113, 0xffff0000, v200
	v_pk_fma_f32 v[108:109], v[112:113], v[36:37], v[108:109]
	v_lshlrev_b32_e32 v114, 16, v201
	v_and_b32_e32 v115, 0xffff0000, v201
	v_pk_fma_f32 v[110:111], v[114:115], v[38:39], v[110:111]
	v_lshlrev_b32_e32 v112, 16, v210
	v_and_b32_e32 v113, 0xffff0000, v210
	v_pk_fma_f32 v[104:105], v[112:113], v[40:41], v[104:105]
	v_lshlrev_b32_e32 v114, 16, v211
	v_and_b32_e32 v115, 0xffff0000, v211
	v_pk_fma_f32 v[106:107], v[114:115], v[42:43], v[106:107]
	v_lshlrev_b32_e32 v112, 16, v212
	v_and_b32_e32 v113, 0xffff0000, v212
	v_pk_fma_f32 v[108:109], v[112:113], v[44:45], v[108:109]
	v_lshlrev_b32_e32 v114, 16, v213
	v_and_b32_e32 v115, 0xffff0000, v213
	v_pk_fma_f32 v[110:111], v[114:115], v[46:47], v[110:111]
	v_lshlrev_b32_e32 v112, 16, v190
	v_and_b32_e32 v113, 0xffff0000, v190
	v_pk_fma_f32 v[104:105], v[112:113], v[48:49], v[104:105]
	v_lshlrev_b32_e32 v114, 16, v191
	v_and_b32_e32 v115, 0xffff0000, v191
	v_pk_fma_f32 v[106:107], v[114:115], v[50:51], v[106:107]
	v_lshlrev_b32_e32 v112, 16, v192
	v_and_b32_e32 v113, 0xffff0000, v192
	v_pk_fma_f32 v[108:109], v[112:113], v[52:53], v[108:109]
	v_lshlrev_b32_e32 v114, 16, v193
	v_and_b32_e32 v115, 0xffff0000, v193
	v_pk_fma_f32 v[110:111], v[114:115], v[54:55], v[110:111]
	v_lshlrev_b32_e32 v112, 16, v202
	v_and_b32_e32 v113, 0xffff0000, v202
	v_pk_fma_f32 v[104:105], v[112:113], v[56:57], v[104:105]
	v_lshlrev_b32_e32 v114, 16, v203
	v_and_b32_e32 v115, 0xffff0000, v203
	v_pk_fma_f32 v[106:107], v[114:115], v[58:59], v[106:107]
	v_lshlrev_b32_e32 v112, 16, v204
	v_and_b32_e32 v113, 0xffff0000, v204
	v_pk_fma_f32 v[108:109], v[112:113], v[60:61], v[108:109]
	v_lshlrev_b32_e32 v114, 16, v205
	v_and_b32_e32 v115, 0xffff0000, v205
	v_pk_fma_f32 v[110:111], v[114:115], v[62:63], v[110:111]
	v_lshlrev_b32_e32 v112, 16, v214
	v_and_b32_e32 v113, 0xffff0000, v214
	v_pk_fma_f32 v[104:105], v[112:113], v[64:65], v[104:105]
	v_lshlrev_b32_e32 v114, 16, v215
	v_and_b32_e32 v115, 0xffff0000, v215
	v_pk_fma_f32 v[106:107], v[114:115], v[66:67], v[106:107]
	v_lshlrev_b32_e32 v112, 16, v216
	v_and_b32_e32 v113, 0xffff0000, v216
	v_pk_fma_f32 v[108:109], v[112:113], v[68:69], v[108:109]
	v_lshlrev_b32_e32 v114, 16, v217
	v_and_b32_e32 v115, 0xffff0000, v217
	v_pk_fma_f32 v[110:111], v[114:115], v[70:71], v[110:111]
	v_mov_b64_e32 v[132:133], s[28:29]
	v_and_b32_e32 v116, 0x7fffffff, v104
	v_and_b32_e32 v117, 0x7fffffff, v105
	v_pk_fma_f32 v[116:117], v[116:117], s[24:25], 1.0 op_sel_hi:[1,0,0]
	v_pk_mul_f32 v[218:219], v[104:105], v[104:105]
	v_rcp_f32_e32 v116, v116
	v_rcp_f32_e32 v117, v117
	v_pk_mul_f32 v[218:219], v[218:219], s[38:39] op_sel_hi:[1,0]
	v_and_b32_e32 v118, 0x7fffffff, v106
	v_and_b32_e32 v119, 0x7fffffff, v107
	v_pk_fma_f32 v[118:119], v[118:119], s[24:25], 1.0 op_sel_hi:[1,0,0]
	v_pk_mul_f32 v[220:221], v[106:107], v[106:107]
	v_rcp_f32_e32 v118, v118
	v_rcp_f32_e32 v119, v119
	v_pk_mul_f32 v[220:221], v[220:221], s[38:39] op_sel_hi:[1,0]
	v_and_b32_e32 v120, 0x7fffffff, v108
	v_and_b32_e32 v121, 0x7fffffff, v109
	v_pk_fma_f32 v[120:121], v[120:121], s[24:25], 1.0 op_sel_hi:[1,0,0]
	v_pk_mul_f32 v[222:223], v[108:109], v[108:109]
	v_rcp_f32_e32 v120, v120
	v_rcp_f32_e32 v121, v121
	v_pk_mul_f32 v[222:223], v[222:223], s[38:39] op_sel_hi:[1,0]
	v_and_b32_e32 v122, 0x7fffffff, v110
	v_and_b32_e32 v123, 0x7fffffff, v111
	v_pk_fma_f32 v[122:123], v[122:123], s[24:25], 1.0 op_sel_hi:[1,0,0]
	v_pk_mul_f32 v[224:225], v[110:111], v[110:111]
	v_rcp_f32_e32 v122, v122
	v_rcp_f32_e32 v123, v123
	v_pk_mul_f32 v[224:225], v[224:225], s[38:39] op_sel_hi:[1,0]
	v_pk_fma_f32 v[124:125], v[116:117], s[26:27], v[132:133] op_sel_hi:[1,0,0]
	v_exp_f32_e32 v218, v218
	v_pk_fma_f32 v[124:125], v[116:117], v[124:125], s[30:31] op_sel_hi:[1,1,0]
	v_exp_f32_e32 v219, v219
	v_pk_fma_f32 v[124:125], v[116:117], v[124:125], s[34:35] op_sel_hi:[1,1,0]
	v_pk_fma_f32 v[124:125], v[116:117], v[124:125], s[36:37] op_sel_hi:[1,1,0]
	v_pk_mul_f32 v[124:125], v[116:117], v[124:125]
	v_pk_fma_f32 v[126:127], v[118:119], s[26:27], v[132:133] op_sel_hi:[1,0,0]
	v_exp_f32_e32 v220, v220
	v_pk_fma_f32 v[126:127], v[118:119], v[126:127], s[30:31] op_sel_hi:[1,1,0]
	v_exp_f32_e32 v221, v221
	v_pk_fma_f32 v[126:127], v[118:119], v[126:127], s[34:35] op_sel_hi:[1,1,0]
	v_pk_fma_f32 v[126:127], v[118:119], v[126:127], s[36:37] op_sel_hi:[1,1,0]
	v_pk_mul_f32 v[126:127], v[118:119], v[126:127]
	v_pk_fma_f32 v[128:129], v[120:121], s[26:27], v[132:133] op_sel_hi:[1,0,0]
	v_exp_f32_e32 v222, v222
	v_pk_fma_f32 v[128:129], v[120:121], v[128:129], s[30:31] op_sel_hi:[1,1,0]
	v_exp_f32_e32 v223, v223
	v_pk_fma_f32 v[128:129], v[120:121], v[128:129], s[34:35] op_sel_hi:[1,1,0]
	v_pk_fma_f32 v[128:129], v[120:121], v[128:129], s[36:37] op_sel_hi:[1,1,0]
	v_pk_mul_f32 v[128:129], v[120:121], v[128:129]
	v_pk_fma_f32 v[130:131], v[122:123], s[26:27], v[132:133] op_sel_hi:[1,0,0]
	v_exp_f32_e32 v224, v224
	v_pk_fma_f32 v[130:131], v[122:123], v[130:131], s[30:31] op_sel_hi:[1,1,0]
	v_exp_f32_e32 v225, v225
	v_pk_fma_f32 v[130:131], v[122:123], v[130:131], s[34:35] op_sel_hi:[1,1,0]
	v_pk_fma_f32 v[130:131], v[122:123], v[130:131], s[36:37] op_sel_hi:[1,1,0]
	v_pk_mul_f32 v[130:131], v[122:123], v[130:131]
	v_pk_mul_f32 v[124:125], v[218:219], v[124:125]
	v_pk_mul_f32 v[218:219], v[104:105], v[124:125]
	v_pk_fma_f32 v[124:125], v[104:105], v[124:125], v[104:105] neg_lo:[1,0,0] neg_hi:[1,0,0]
	v_cmp_gt_f32_e64 s[8:9], 0, v104
	v_cmp_gt_f32_e64 s[22:23], 0, v105
	v_lshlrev_b32_e32 v112, 16, v92
	v_and_b32_e32 v113, 0xffff0000, v92
	v_cndmask_b32_e64 v104, v124, v218, s[8:9]
	v_cndmask_b32_e64 v105, v125, v219, s[22:23]
	v_pk_mul_f32 v[104:105], v[104:105], v[112:113]
	v_cvt_pk_bf16_f32 v226, v104, v105
	v_pk_mul_f32 v[126:127], v[220:221], v[126:127]
	v_pk_mul_f32 v[220:221], v[106:107], v[126:127]
	v_pk_fma_f32 v[126:127], v[106:107], v[126:127], v[106:107] neg_lo:[1,0,0] neg_hi:[1,0,0]
	v_cmp_gt_f32_e64 s[8:9], 0, v106
	v_cmp_gt_f32_e64 s[22:23], 0, v107
	v_lshlrev_b32_e32 v112, 16, v93
	v_and_b32_e32 v113, 0xffff0000, v93
	v_cndmask_b32_e64 v106, v126, v220, s[8:9]
	v_cndmask_b32_e64 v107, v127, v221, s[22:23]
	v_pk_mul_f32 v[106:107], v[106:107], v[112:113]
	v_cvt_pk_bf16_f32 v227, v106, v107
	v_pk_mul_f32 v[128:129], v[222:223], v[128:129]
	v_pk_mul_f32 v[222:223], v[108:109], v[128:129]
	v_pk_fma_f32 v[128:129], v[108:109], v[128:129], v[108:109] neg_lo:[1,0,0] neg_hi:[1,0,0]
	v_cmp_gt_f32_e64 s[8:9], 0, v108
	v_cmp_gt_f32_e64 s[22:23], 0, v109
	v_lshlrev_b32_e32 v112, 16, v94
	v_and_b32_e32 v113, 0xffff0000, v94
	v_cndmask_b32_e64 v108, v128, v222, s[8:9]
	v_cndmask_b32_e64 v109, v129, v223, s[22:23]
	v_pk_mul_f32 v[108:109], v[108:109], v[112:113]
	v_cvt_pk_bf16_f32 v228, v108, v109
	v_pk_mul_f32 v[130:131], v[224:225], v[130:131]
	v_pk_mul_f32 v[224:225], v[110:111], v[130:131]
	v_pk_fma_f32 v[130:131], v[110:111], v[130:131], v[110:111] neg_lo:[1,0,0] neg_hi:[1,0,0]
	v_cmp_gt_f32_e64 s[8:9], 0, v110
	v_cmp_gt_f32_e64 s[22:23], 0, v111
	v_lshlrev_b32_e32 v112, 16, v95
	v_and_b32_e32 v113, 0xffff0000, v95
	v_cndmask_b32_e64 v110, v130, v224, s[8:9]
	v_cndmask_b32_e64 v111, v131, v225, s[22:23]
	v_pk_mul_f32 v[110:111], v[110:111], v[112:113]
	v_cvt_pk_bf16_f32 v229, v110, v111
	global_store_dwordx4 v140, v[226:229], s[14:15]
	v_add_u32_e32 v140, 0x2c00, v140
	global_load_dwordx4 v[182:185], v136, s[14:15]
	global_load_dwordx4 v[186:189], v137, s[14:15]
	global_load_dwordx4 v[190:193], v138, s[14:15]
	v_add_u32_e32 v136, 0x2c00, v136
	v_add_u32_e32 v137, 0x2c00, v137
	v_add_u32_e32 v138, 0x2c00, v138
	global_load_dwordx4 v[88:91], v139, s[14:15]
	v_add_u32_e32 v139, 0x2c00, v139
	s_waitcnt vmcnt(16)
	v_mov_b64_e32 v[104:105], v[72:73]
	v_mov_b64_e32 v[106:107], v[74:75]
	v_mov_b64_e32 v[108:109], v[76:77]
	v_mov_b64_e32 v[110:111], v[78:79]
	v_lshlrev_b32_e32 v112, 16, v194
	v_and_b32_e32 v113, 0xffff0000, v194
	v_pk_fma_f32 v[104:105], v[112:113], v[0:1], v[104:105]
	v_lshlrev_b32_e32 v114, 16, v195
	v_and_b32_e32 v115, 0xffff0000, v195
	v_pk_fma_f32 v[106:107], v[114:115], v[2:3], v[106:107]
	v_lshlrev_b32_e32 v112, 16, v196
	v_and_b32_e32 v113, 0xffff0000, v196
	v_pk_fma_f32 v[108:109], v[112:113], v[4:5], v[108:109]
	v_lshlrev_b32_e32 v114, 16, v197
	v_and_b32_e32 v115, 0xffff0000, v197
	v_pk_fma_f32 v[110:111], v[114:115], v[6:7], v[110:111]
	v_lshlrev_b32_e32 v112, 16, v206
	v_and_b32_e32 v113, 0xffff0000, v206
	v_pk_fma_f32 v[104:105], v[112:113], v[8:9], v[104:105]
	v_lshlrev_b32_e32 v114, 16, v207
	v_and_b32_e32 v115, 0xffff0000, v207
	v_pk_fma_f32 v[106:107], v[114:115], v[10:11], v[106:107]
	v_lshlrev_b32_e32 v112, 16, v208
	v_and_b32_e32 v113, 0xffff0000, v208
	v_pk_fma_f32 v[108:109], v[112:113], v[12:13], v[108:109]
	v_lshlrev_b32_e32 v114, 16, v209
	v_and_b32_e32 v115, 0xffff0000, v209
	v_pk_fma_f32 v[110:111], v[114:115], v[14:15], v[110:111]
	v_lshlrev_b32_e32 v112, 16, v146
	v_and_b32_e32 v113, 0xffff0000, v146
	v_pk_fma_f32 v[104:105], v[112:113], v[16:17], v[104:105]
	v_lshlrev_b32_e32 v114, 16, v147
	v_and_b32_e32 v115, 0xffff0000, v147
	v_pk_fma_f32 v[106:107], v[114:115], v[18:19], v[106:107]
	v_lshlrev_b32_e32 v112, 16, v148
	v_and_b32_e32 v113, 0xffff0000, v148
	v_pk_fma_f32 v[108:109], v[112:113], v[20:21], v[108:109]
	v_lshlrev_b32_e32 v114, 16, v149
	v_and_b32_e32 v115, 0xffff0000, v149
	v_pk_fma_f32 v[110:111], v[114:115], v[22:23], v[110:111]
	v_lshlrev_b32_e32 v112, 16, v198
	v_and_b32_e32 v113, 0xffff0000, v198
	v_pk_fma_f32 v[104:105], v[112:113], v[24:25], v[104:105]
	v_lshlrev_b32_e32 v114, 16, v199
	v_and_b32_e32 v115, 0xffff0000, v199
	v_pk_fma_f32 v[106:107], v[114:115], v[26:27], v[106:107]
	v_lshlrev_b32_e32 v112, 16, v200
	v_and_b32_e32 v113, 0xffff0000, v200
	v_pk_fma_f32 v[108:109], v[112:113], v[28:29], v[108:109]
	v_lshlrev_b32_e32 v114, 16, v201
	v_and_b32_e32 v115, 0xffff0000, v201
	v_pk_fma_f32 v[110:111], v[114:115], v[30:31], v[110:111]
	v_lshlrev_b32_e32 v112, 16, v210
	v_and_b32_e32 v113, 0xffff0000, v210
	v_pk_fma_f32 v[104:105], v[112:113], v[32:33], v[104:105]
	v_lshlrev_b32_e32 v114, 16, v211
	v_and_b32_e32 v115, 0xffff0000, v211
	v_pk_fma_f32 v[106:107], v[114:115], v[34:35], v[106:107]
	v_lshlrev_b32_e32 v112, 16, v212
	v_and_b32_e32 v113, 0xffff0000, v212
	v_pk_fma_f32 v[108:109], v[112:113], v[36:37], v[108:109]
	v_lshlrev_b32_e32 v114, 16, v213
	v_and_b32_e32 v115, 0xffff0000, v213
	v_pk_fma_f32 v[110:111], v[114:115], v[38:39], v[110:111]
	v_lshlrev_b32_e32 v112, 16, v150
	v_and_b32_e32 v113, 0xffff0000, v150
	v_pk_fma_f32 v[104:105], v[112:113], v[40:41], v[104:105]
	v_lshlrev_b32_e32 v114, 16, v151
	v_and_b32_e32 v115, 0xffff0000, v151
	v_pk_fma_f32 v[106:107], v[114:115], v[42:43], v[106:107]
	v_lshlrev_b32_e32 v112, 16, v152
	v_and_b32_e32 v113, 0xffff0000, v152
	v_pk_fma_f32 v[108:109], v[112:113], v[44:45], v[108:109]
	v_lshlrev_b32_e32 v114, 16, v153
	v_and_b32_e32 v115, 0xffff0000, v153
	v_pk_fma_f32 v[110:111], v[114:115], v[46:47], v[110:111]
	v_lshlrev_b32_e32 v112, 16, v202
	v_and_b32_e32 v113, 0xffff0000, v202
	v_pk_fma_f32 v[104:105], v[112:113], v[48:49], v[104:105]
	v_lshlrev_b32_e32 v114, 16, v203
	v_and_b32_e32 v115, 0xffff0000, v203
	v_pk_fma_f32 v[106:107], v[114:115], v[50:51], v[106:107]
	v_lshlrev_b32_e32 v112, 16, v204
	v_and_b32_e32 v113, 0xffff0000, v204
	v_pk_fma_f32 v[108:109], v[112:113], v[52:53], v[108:109]
	v_lshlrev_b32_e32 v114, 16, v205
	v_and_b32_e32 v115, 0xffff0000, v205
	v_pk_fma_f32 v[110:111], v[114:115], v[54:55], v[110:111]
	v_lshlrev_b32_e32 v112, 16, v214
	v_and_b32_e32 v113, 0xffff0000, v214
	v_pk_fma_f32 v[104:105], v[112:113], v[56:57], v[104:105]
	v_lshlrev_b32_e32 v114, 16, v215
	v_and_b32_e32 v115, 0xffff0000, v215
	v_pk_fma_f32 v[106:107], v[114:115], v[58:59], v[106:107]
	v_lshlrev_b32_e32 v112, 16, v216
	v_and_b32_e32 v113, 0xffff0000, v216
	v_pk_fma_f32 v[108:109], v[112:113], v[60:61], v[108:109]
	v_lshlrev_b32_e32 v114, 16, v217
	v_and_b32_e32 v115, 0xffff0000, v217
	v_pk_fma_f32 v[110:111], v[114:115], v[62:63], v[110:111]
	v_lshlrev_b32_e32 v112, 16, v154
	v_and_b32_e32 v113, 0xffff0000, v154
	v_pk_fma_f32 v[104:105], v[112:113], v[64:65], v[104:105]
	v_lshlrev_b32_e32 v114, 16, v155
	v_and_b32_e32 v115, 0xffff0000, v155
	v_pk_fma_f32 v[106:107], v[114:115], v[66:67], v[106:107]
	v_lshlrev_b32_e32 v112, 16, v156
	v_and_b32_e32 v113, 0xffff0000, v156
	v_pk_fma_f32 v[108:109], v[112:113], v[68:69], v[108:109]
	v_lshlrev_b32_e32 v114, 16, v157
	v_and_b32_e32 v115, 0xffff0000, v157
	v_pk_fma_f32 v[110:111], v[114:115], v[70:71], v[110:111]
	v_mov_b64_e32 v[132:133], s[28:29]
	v_and_b32_e32 v116, 0x7fffffff, v104
	v_and_b32_e32 v117, 0x7fffffff, v105
	v_pk_fma_f32 v[116:117], v[116:117], s[24:25], 1.0 op_sel_hi:[1,0,0]
	v_pk_mul_f32 v[218:219], v[104:105], v[104:105]
	v_rcp_f32_e32 v116, v116
	v_rcp_f32_e32 v117, v117
	v_pk_mul_f32 v[218:219], v[218:219], s[38:39] op_sel_hi:[1,0]
	v_and_b32_e32 v118, 0x7fffffff, v106
	v_and_b32_e32 v119, 0x7fffffff, v107
	v_pk_fma_f32 v[118:119], v[118:119], s[24:25], 1.0 op_sel_hi:[1,0,0]
	v_pk_mul_f32 v[220:221], v[106:107], v[106:107]
	v_rcp_f32_e32 v118, v118
	v_rcp_f32_e32 v119, v119
	v_pk_mul_f32 v[220:221], v[220:221], s[38:39] op_sel_hi:[1,0]
	v_and_b32_e32 v120, 0x7fffffff, v108
	v_and_b32_e32 v121, 0x7fffffff, v109
	v_pk_fma_f32 v[120:121], v[120:121], s[24:25], 1.0 op_sel_hi:[1,0,0]
	v_pk_mul_f32 v[222:223], v[108:109], v[108:109]
	v_rcp_f32_e32 v120, v120
	v_rcp_f32_e32 v121, v121
	v_pk_mul_f32 v[222:223], v[222:223], s[38:39] op_sel_hi:[1,0]
	v_and_b32_e32 v122, 0x7fffffff, v110
	v_and_b32_e32 v123, 0x7fffffff, v111
	v_pk_fma_f32 v[122:123], v[122:123], s[24:25], 1.0 op_sel_hi:[1,0,0]
	v_pk_mul_f32 v[224:225], v[110:111], v[110:111]
	v_rcp_f32_e32 v122, v122
	v_rcp_f32_e32 v123, v123
	v_pk_mul_f32 v[224:225], v[224:225], s[38:39] op_sel_hi:[1,0]
	v_pk_fma_f32 v[124:125], v[116:117], s[26:27], v[132:133] op_sel_hi:[1,0,0]
	v_exp_f32_e32 v218, v218
	v_pk_fma_f32 v[124:125], v[116:117], v[124:125], s[30:31] op_sel_hi:[1,1,0]
	v_exp_f32_e32 v219, v219
	v_pk_fma_f32 v[124:125], v[116:117], v[124:125], s[34:35] op_sel_hi:[1,1,0]
	v_pk_fma_f32 v[124:125], v[116:117], v[124:125], s[36:37] op_sel_hi:[1,1,0]
	v_pk_mul_f32 v[124:125], v[116:117], v[124:125]
	v_pk_fma_f32 v[126:127], v[118:119], s[26:27], v[132:133] op_sel_hi:[1,0,0]
	v_exp_f32_e32 v220, v220
	v_pk_fma_f32 v[126:127], v[118:119], v[126:127], s[30:31] op_sel_hi:[1,1,0]
	v_exp_f32_e32 v221, v221
	v_pk_fma_f32 v[126:127], v[118:119], v[126:127], s[34:35] op_sel_hi:[1,1,0]
	v_pk_fma_f32 v[126:127], v[118:119], v[126:127], s[36:37] op_sel_hi:[1,1,0]
	v_pk_mul_f32 v[126:127], v[118:119], v[126:127]
	v_pk_fma_f32 v[128:129], v[120:121], s[26:27], v[132:133] op_sel_hi:[1,0,0]
	v_exp_f32_e32 v222, v222
	v_pk_fma_f32 v[128:129], v[120:121], v[128:129], s[30:31] op_sel_hi:[1,1,0]
	v_exp_f32_e32 v223, v223
	v_pk_fma_f32 v[128:129], v[120:121], v[128:129], s[34:35] op_sel_hi:[1,1,0]
	v_pk_fma_f32 v[128:129], v[120:121], v[128:129], s[36:37] op_sel_hi:[1,1,0]
	v_pk_mul_f32 v[128:129], v[120:121], v[128:129]
	v_pk_fma_f32 v[130:131], v[122:123], s[26:27], v[132:133] op_sel_hi:[1,0,0]
	v_exp_f32_e32 v224, v224
	v_pk_fma_f32 v[130:131], v[122:123], v[130:131], s[30:31] op_sel_hi:[1,1,0]
	v_exp_f32_e32 v225, v225
	v_pk_fma_f32 v[130:131], v[122:123], v[130:131], s[34:35] op_sel_hi:[1,1,0]
	v_pk_fma_f32 v[130:131], v[122:123], v[130:131], s[36:37] op_sel_hi:[1,1,0]
	v_pk_mul_f32 v[130:131], v[122:123], v[130:131]
	v_pk_mul_f32 v[124:125], v[218:219], v[124:125]
	v_pk_mul_f32 v[218:219], v[104:105], v[124:125]
	v_pk_fma_f32 v[124:125], v[104:105], v[124:125], v[104:105] neg_lo:[1,0,0] neg_hi:[1,0,0]
	v_cmp_gt_f32_e64 s[8:9], 0, v104
	v_cmp_gt_f32_e64 s[22:23], 0, v105
	v_lshlrev_b32_e32 v112, 16, v96
	v_and_b32_e32 v113, 0xffff0000, v96
	v_cndmask_b32_e64 v104, v124, v218, s[8:9]
	v_cndmask_b32_e64 v105, v125, v219, s[22:23]
	v_pk_mul_f32 v[104:105], v[104:105], v[112:113]
	v_cvt_pk_bf16_f32 v226, v104, v105
	v_pk_mul_f32 v[126:127], v[220:221], v[126:127]
	v_pk_mul_f32 v[220:221], v[106:107], v[126:127]
	v_pk_fma_f32 v[126:127], v[106:107], v[126:127], v[106:107] neg_lo:[1,0,0] neg_hi:[1,0,0]
	v_cmp_gt_f32_e64 s[8:9], 0, v106
	v_cmp_gt_f32_e64 s[22:23], 0, v107
	v_lshlrev_b32_e32 v112, 16, v97
	v_and_b32_e32 v113, 0xffff0000, v97
	v_cndmask_b32_e64 v106, v126, v220, s[8:9]
	v_cndmask_b32_e64 v107, v127, v221, s[22:23]
	v_pk_mul_f32 v[106:107], v[106:107], v[112:113]
	v_cvt_pk_bf16_f32 v227, v106, v107
	v_pk_mul_f32 v[128:129], v[222:223], v[128:129]
	v_pk_mul_f32 v[222:223], v[108:109], v[128:129]
	v_pk_fma_f32 v[128:129], v[108:109], v[128:129], v[108:109] neg_lo:[1,0,0] neg_hi:[1,0,0]
	v_cmp_gt_f32_e64 s[8:9], 0, v108
	v_cmp_gt_f32_e64 s[22:23], 0, v109
	v_lshlrev_b32_e32 v112, 16, v98
	v_and_b32_e32 v113, 0xffff0000, v98
	v_cndmask_b32_e64 v108, v128, v222, s[8:9]
	v_cndmask_b32_e64 v109, v129, v223, s[22:23]
	v_pk_mul_f32 v[108:109], v[108:109], v[112:113]
	v_cvt_pk_bf16_f32 v228, v108, v109
	v_pk_mul_f32 v[130:131], v[224:225], v[130:131]
	v_pk_mul_f32 v[224:225], v[110:111], v[130:131]
	v_pk_fma_f32 v[130:131], v[110:111], v[130:131], v[110:111] neg_lo:[1,0,0] neg_hi:[1,0,0]
	v_cmp_gt_f32_e64 s[8:9], 0, v110
	v_cmp_gt_f32_e64 s[22:23], 0, v111
	v_lshlrev_b32_e32 v112, 16, v99
	v_and_b32_e32 v113, 0xffff0000, v99
	v_cndmask_b32_e64 v110, v130, v224, s[8:9]
	v_cndmask_b32_e64 v111, v131, v225, s[22:23]
	v_pk_mul_f32 v[110:111], v[110:111], v[112:113]
	v_cvt_pk_bf16_f32 v229, v110, v111
	global_store_dwordx4 v140, v[226:229], s[14:15]
	v_add_u32_e32 v140, 0x2c00, v140
	global_load_dwordx4 v[194:197], v136, s[14:15]
	global_load_dwordx4 v[198:201], v137, s[14:15]
	global_load_dwordx4 v[202:205], v138, s[14:15]
	v_add_u32_e32 v136, 0x2c00, v136
	v_add_u32_e32 v137, 0x2c00, v137
	v_add_u32_e32 v138, 0x2c00, v138
	global_load_dwordx4 v[92:95], v139, s[14:15]
	v_add_u32_e32 v139, 0x2c00, v139
	s_waitcnt vmcnt(16)
	v_mov_b64_e32 v[104:105], v[72:73]
	v_mov_b64_e32 v[106:107], v[74:75]
	v_mov_b64_e32 v[108:109], v[76:77]
	v_mov_b64_e32 v[110:111], v[78:79]
	v_lshlrev_b32_e32 v112, 16, v206
	v_and_b32_e32 v113, 0xffff0000, v206
	v_pk_fma_f32 v[104:105], v[112:113], v[0:1], v[104:105]
	v_lshlrev_b32_e32 v114, 16, v207
	v_and_b32_e32 v115, 0xffff0000, v207
	v_pk_fma_f32 v[106:107], v[114:115], v[2:3], v[106:107]
	v_lshlrev_b32_e32 v112, 16, v208
	v_and_b32_e32 v113, 0xffff0000, v208
	v_pk_fma_f32 v[108:109], v[112:113], v[4:5], v[108:109]
	v_lshlrev_b32_e32 v114, 16, v209
	v_and_b32_e32 v115, 0xffff0000, v209
	v_pk_fma_f32 v[110:111], v[114:115], v[6:7], v[110:111]
	v_lshlrev_b32_e32 v112, 16, v146
	v_and_b32_e32 v113, 0xffff0000, v146
	v_pk_fma_f32 v[104:105], v[112:113], v[8:9], v[104:105]
	v_lshlrev_b32_e32 v114, 16, v147
	v_and_b32_e32 v115, 0xffff0000, v147
	v_pk_fma_f32 v[106:107], v[114:115], v[10:11], v[106:107]
	v_lshlrev_b32_e32 v112, 16, v148
	v_and_b32_e32 v113, 0xffff0000, v148
	v_pk_fma_f32 v[108:109], v[112:113], v[12:13], v[108:109]
	v_lshlrev_b32_e32 v114, 16, v149
	v_and_b32_e32 v115, 0xffff0000, v149
	v_pk_fma_f32 v[110:111], v[114:115], v[14:15], v[110:111]
	v_lshlrev_b32_e32 v112, 16, v158
	v_and_b32_e32 v113, 0xffff0000, v158
	v_pk_fma_f32 v[104:105], v[112:113], v[16:17], v[104:105]
	v_lshlrev_b32_e32 v114, 16, v159
	v_and_b32_e32 v115, 0xffff0000, v159
	v_pk_fma_f32 v[106:107], v[114:115], v[18:19], v[106:107]
	v_lshlrev_b32_e32 v112, 16, v160
	v_and_b32_e32 v113, 0xffff0000, v160
	v_pk_fma_f32 v[108:109], v[112:113], v[20:21], v[108:109]
	v_lshlrev_b32_e32 v114, 16, v161
	v_and_b32_e32 v115, 0xffff0000, v161
	v_pk_fma_f32 v[110:111], v[114:115], v[22:23], v[110:111]
	v_lshlrev_b32_e32 v112, 16, v210
	v_and_b32_e32 v113, 0xffff0000, v210
	v_pk_fma_f32 v[104:105], v[112:113], v[24:25], v[104:105]
	v_lshlrev_b32_e32 v114, 16, v211
	v_and_b32_e32 v115, 0xffff0000, v211
	v_pk_fma_f32 v[106:107], v[114:115], v[26:27], v[106:107]
	v_lshlrev_b32_e32 v112, 16, v212
	v_and_b32_e32 v113, 0xffff0000, v212
	v_pk_fma_f32 v[108:109], v[112:113], v[28:29], v[108:109]
	v_lshlrev_b32_e32 v114, 16, v213
	v_and_b32_e32 v115, 0xffff0000, v213
	v_pk_fma_f32 v[110:111], v[114:115], v[30:31], v[110:111]
	v_lshlrev_b32_e32 v112, 16, v150
	v_and_b32_e32 v113, 0xffff0000, v150
	v_pk_fma_f32 v[104:105], v[112:113], v[32:33], v[104:105]
	v_lshlrev_b32_e32 v114, 16, v151
	v_and_b32_e32 v115, 0xffff0000, v151
	v_pk_fma_f32 v[106:107], v[114:115], v[34:35], v[106:107]
	v_lshlrev_b32_e32 v112, 16, v152
	v_and_b32_e32 v113, 0xffff0000, v152
	v_pk_fma_f32 v[108:109], v[112:113], v[36:37], v[108:109]
	v_lshlrev_b32_e32 v114, 16, v153
	v_and_b32_e32 v115, 0xffff0000, v153
	v_pk_fma_f32 v[110:111], v[114:115], v[38:39], v[110:111]
	v_lshlrev_b32_e32 v112, 16, v162
	v_and_b32_e32 v113, 0xffff0000, v162
	v_pk_fma_f32 v[104:105], v[112:113], v[40:41], v[104:105]
	v_lshlrev_b32_e32 v114, 16, v163
	v_and_b32_e32 v115, 0xffff0000, v163
	v_pk_fma_f32 v[106:107], v[114:115], v[42:43], v[106:107]
	v_lshlrev_b32_e32 v112, 16, v164
	v_and_b32_e32 v113, 0xffff0000, v164
	v_pk_fma_f32 v[108:109], v[112:113], v[44:45], v[108:109]
	v_lshlrev_b32_e32 v114, 16, v165
	v_and_b32_e32 v115, 0xffff0000, v165
	v_pk_fma_f32 v[110:111], v[114:115], v[46:47], v[110:111]
	v_lshlrev_b32_e32 v112, 16, v214
	v_and_b32_e32 v113, 0xffff0000, v214
	v_pk_fma_f32 v[104:105], v[112:113], v[48:49], v[104:105]
	v_lshlrev_b32_e32 v114, 16, v215
	v_and_b32_e32 v115, 0xffff0000, v215
	v_pk_fma_f32 v[106:107], v[114:115], v[50:51], v[106:107]
	v_lshlrev_b32_e32 v112, 16, v216
	v_and_b32_e32 v113, 0xffff0000, v216
	v_pk_fma_f32 v[108:109], v[112:113], v[52:53], v[108:109]
	v_lshlrev_b32_e32 v114, 16, v217
	v_and_b32_e32 v115, 0xffff0000, v217
	v_pk_fma_f32 v[110:111], v[114:115], v[54:55], v[110:111]
	v_lshlrev_b32_e32 v112, 16, v154
	v_and_b32_e32 v113, 0xffff0000, v154
	v_pk_fma_f32 v[104:105], v[112:113], v[56:57], v[104:105]
	v_lshlrev_b32_e32 v114, 16, v155
	v_and_b32_e32 v115, 0xffff0000, v155
	v_pk_fma_f32 v[106:107], v[114:115], v[58:59], v[106:107]
	v_lshlrev_b32_e32 v112, 16, v156
	v_and_b32_e32 v113, 0xffff0000, v156
	v_pk_fma_f32 v[108:109], v[112:113], v[60:61], v[108:109]
	v_lshlrev_b32_e32 v114, 16, v157
	v_and_b32_e32 v115, 0xffff0000, v157
	v_pk_fma_f32 v[110:111], v[114:115], v[62:63], v[110:111]
	v_lshlrev_b32_e32 v112, 16, v166
	v_and_b32_e32 v113, 0xffff0000, v166
	v_pk_fma_f32 v[104:105], v[112:113], v[64:65], v[104:105]
	v_lshlrev_b32_e32 v114, 16, v167
	v_and_b32_e32 v115, 0xffff0000, v167
	v_pk_fma_f32 v[106:107], v[114:115], v[66:67], v[106:107]
	v_lshlrev_b32_e32 v112, 16, v168
	v_and_b32_e32 v113, 0xffff0000, v168
	v_pk_fma_f32 v[108:109], v[112:113], v[68:69], v[108:109]
	v_lshlrev_b32_e32 v114, 16, v169
	v_and_b32_e32 v115, 0xffff0000, v169
	v_pk_fma_f32 v[110:111], v[114:115], v[70:71], v[110:111]
	v_mov_b64_e32 v[132:133], s[28:29]
	v_and_b32_e32 v116, 0x7fffffff, v104
	v_and_b32_e32 v117, 0x7fffffff, v105
	v_pk_fma_f32 v[116:117], v[116:117], s[24:25], 1.0 op_sel_hi:[1,0,0]
	v_pk_mul_f32 v[218:219], v[104:105], v[104:105]
	v_rcp_f32_e32 v116, v116
	v_rcp_f32_e32 v117, v117
	v_pk_mul_f32 v[218:219], v[218:219], s[38:39] op_sel_hi:[1,0]
	v_and_b32_e32 v118, 0x7fffffff, v106
	v_and_b32_e32 v119, 0x7fffffff, v107
	v_pk_fma_f32 v[118:119], v[118:119], s[24:25], 1.0 op_sel_hi:[1,0,0]
	v_pk_mul_f32 v[220:221], v[106:107], v[106:107]
	v_rcp_f32_e32 v118, v118
	v_rcp_f32_e32 v119, v119
	v_pk_mul_f32 v[220:221], v[220:221], s[38:39] op_sel_hi:[1,0]
	v_and_b32_e32 v120, 0x7fffffff, v108
	v_and_b32_e32 v121, 0x7fffffff, v109
	v_pk_fma_f32 v[120:121], v[120:121], s[24:25], 1.0 op_sel_hi:[1,0,0]
	v_pk_mul_f32 v[222:223], v[108:109], v[108:109]
	v_rcp_f32_e32 v120, v120
	v_rcp_f32_e32 v121, v121
	v_pk_mul_f32 v[222:223], v[222:223], s[38:39] op_sel_hi:[1,0]
	v_and_b32_e32 v122, 0x7fffffff, v110
	v_and_b32_e32 v123, 0x7fffffff, v111
	v_pk_fma_f32 v[122:123], v[122:123], s[24:25], 1.0 op_sel_hi:[1,0,0]
	v_pk_mul_f32 v[224:225], v[110:111], v[110:111]
	v_rcp_f32_e32 v122, v122
	v_rcp_f32_e32 v123, v123
	v_pk_mul_f32 v[224:225], v[224:225], s[38:39] op_sel_hi:[1,0]
	v_pk_fma_f32 v[124:125], v[116:117], s[26:27], v[132:133] op_sel_hi:[1,0,0]
	v_exp_f32_e32 v218, v218
	v_pk_fma_f32 v[124:125], v[116:117], v[124:125], s[30:31] op_sel_hi:[1,1,0]
	v_exp_f32_e32 v219, v219
	v_pk_fma_f32 v[124:125], v[116:117], v[124:125], s[34:35] op_sel_hi:[1,1,0]
	v_pk_fma_f32 v[124:125], v[116:117], v[124:125], s[36:37] op_sel_hi:[1,1,0]
	v_pk_mul_f32 v[124:125], v[116:117], v[124:125]
	v_pk_fma_f32 v[126:127], v[118:119], s[26:27], v[132:133] op_sel_hi:[1,0,0]
	v_exp_f32_e32 v220, v220
	v_pk_fma_f32 v[126:127], v[118:119], v[126:127], s[30:31] op_sel_hi:[1,1,0]
	v_exp_f32_e32 v221, v221
	v_pk_fma_f32 v[126:127], v[118:119], v[126:127], s[34:35] op_sel_hi:[1,1,0]
	v_pk_fma_f32 v[126:127], v[118:119], v[126:127], s[36:37] op_sel_hi:[1,1,0]
	v_pk_mul_f32 v[126:127], v[118:119], v[126:127]
	v_pk_fma_f32 v[128:129], v[120:121], s[26:27], v[132:133] op_sel_hi:[1,0,0]
	v_exp_f32_e32 v222, v222
	v_pk_fma_f32 v[128:129], v[120:121], v[128:129], s[30:31] op_sel_hi:[1,1,0]
	v_exp_f32_e32 v223, v223
	v_pk_fma_f32 v[128:129], v[120:121], v[128:129], s[34:35] op_sel_hi:[1,1,0]
	v_pk_fma_f32 v[128:129], v[120:121], v[128:129], s[36:37] op_sel_hi:[1,1,0]
	v_pk_mul_f32 v[128:129], v[120:121], v[128:129]
	v_pk_fma_f32 v[130:131], v[122:123], s[26:27], v[132:133] op_sel_hi:[1,0,0]
	v_exp_f32_e32 v224, v224
	v_pk_fma_f32 v[130:131], v[122:123], v[130:131], s[30:31] op_sel_hi:[1,1,0]
	v_exp_f32_e32 v225, v225
	v_pk_fma_f32 v[130:131], v[122:123], v[130:131], s[34:35] op_sel_hi:[1,1,0]
	v_pk_fma_f32 v[130:131], v[122:123], v[130:131], s[36:37] op_sel_hi:[1,1,0]
	v_pk_mul_f32 v[130:131], v[122:123], v[130:131]
	v_pk_mul_f32 v[124:125], v[218:219], v[124:125]
	v_pk_mul_f32 v[218:219], v[104:105], v[124:125]
	v_pk_fma_f32 v[124:125], v[104:105], v[124:125], v[104:105] neg_lo:[1,0,0] neg_hi:[1,0,0]
	v_cmp_gt_f32_e64 s[8:9], 0, v104
	v_cmp_gt_f32_e64 s[22:23], 0, v105
	v_lshlrev_b32_e32 v112, 16, v100
	v_and_b32_e32 v113, 0xffff0000, v100
	v_cndmask_b32_e64 v104, v124, v218, s[8:9]
	v_cndmask_b32_e64 v105, v125, v219, s[22:23]
	v_pk_mul_f32 v[104:105], v[104:105], v[112:113]
	v_cvt_pk_bf16_f32 v226, v104, v105
	v_pk_mul_f32 v[126:127], v[220:221], v[126:127]
	v_pk_mul_f32 v[220:221], v[106:107], v[126:127]
	v_pk_fma_f32 v[126:127], v[106:107], v[126:127], v[106:107] neg_lo:[1,0,0] neg_hi:[1,0,0]
	v_cmp_gt_f32_e64 s[8:9], 0, v106
	v_cmp_gt_f32_e64 s[22:23], 0, v107
	v_lshlrev_b32_e32 v112, 16, v101
	v_and_b32_e32 v113, 0xffff0000, v101
	v_cndmask_b32_e64 v106, v126, v220, s[8:9]
	v_cndmask_b32_e64 v107, v127, v221, s[22:23]
	v_pk_mul_f32 v[106:107], v[106:107], v[112:113]
	v_cvt_pk_bf16_f32 v227, v106, v107
	v_pk_mul_f32 v[128:129], v[222:223], v[128:129]
	v_pk_mul_f32 v[222:223], v[108:109], v[128:129]
	v_pk_fma_f32 v[128:129], v[108:109], v[128:129], v[108:109] neg_lo:[1,0,0] neg_hi:[1,0,0]
	v_cmp_gt_f32_e64 s[8:9], 0, v108
	v_cmp_gt_f32_e64 s[22:23], 0, v109
	v_lshlrev_b32_e32 v112, 16, v102
	v_and_b32_e32 v113, 0xffff0000, v102
	v_cndmask_b32_e64 v108, v128, v222, s[8:9]
	v_cndmask_b32_e64 v109, v129, v223, s[22:23]
	v_pk_mul_f32 v[108:109], v[108:109], v[112:113]
	v_cvt_pk_bf16_f32 v228, v108, v109
	v_pk_mul_f32 v[130:131], v[224:225], v[130:131]
	v_pk_mul_f32 v[224:225], v[110:111], v[130:131]
	v_pk_fma_f32 v[130:131], v[110:111], v[130:131], v[110:111] neg_lo:[1,0,0] neg_hi:[1,0,0]
	v_cmp_gt_f32_e64 s[8:9], 0, v110
	v_cmp_gt_f32_e64 s[22:23], 0, v111
	v_lshlrev_b32_e32 v112, 16, v103
	v_and_b32_e32 v113, 0xffff0000, v103
	v_cndmask_b32_e64 v110, v130, v224, s[8:9]
	v_cndmask_b32_e64 v111, v131, v225, s[22:23]
	v_pk_mul_f32 v[110:111], v[110:111], v[112:113]
	v_cvt_pk_bf16_f32 v229, v110, v111
	global_store_dwordx4 v140, v[226:229], s[14:15]
	v_add_u32_e32 v140, 0x2c00, v140
	s_mov_b32 s21, 4
